# P5: epilogue of non-final tiles folded into the K-loop (row groups 0-3 inside the 4th segment of the last BODY, groups 4-7 inside the 1st segment of the next tile's first BODY), no alignment barriers
# baseline (speedup 1.0000x reference)
;     __device__ __forceinline__ unsigned voffA(int R, int C) const { return (unsigned)(R * lda + C) * 2u; }
;     __device__ __forceinline__ unsigned voffB(int R, int C) const { return (unsigned)(R * ldb + C) * 2u; }
;     __device__ __forceinline__ const char* a(const Unit& u) const { return (const char*)A + (size_t)u.pm * 2 * hA(); }
;     __device__ __forceinline__ const char* b(const Unit& u) const { return (const char*)Bt + (size_t)u.pn * 2 * hB() + (size_t)(u.pm >> gshift) * goff; }
;     __device__ __forceinline__ unsigned voffA(int R, int C) const { return (unsigned)(R * 256 + C) * 2u; }
;     __device__ __forceinline__ unsigned voffB(int R, int C) const { return (unsigned)((256 * (R & 15) + (R >> 4)) * 1024 + C) * 2u; }
;     __device__ __forceinline__ const char* a(const Unit& u) const { return (const char*)A + (size_t)u.pm * 2 * hA(); }
;     __device__ __forceinline__ const char* b(const Unit& u) const { return (const char*)Bt + (size_t)((u.pn >> 4) * 4096 + (u.pn & 15) * 16) * 1024 * 2 + (size_t)(u.pm >> 1) * 512; }
;     __device__ __forceinline__ const char* a(const Unit&) const { return (const char*)A; }
;     __device__ __forceinline__ void operator()(const f32x4 (&acc)[2][2][4][2], const Unit& u, int wr, int wc, int fr, int fq) const {
;     ...
;         float rsv[2][4];
; #pragma unroll
;         for (int ai = 0; ai < 2; ++ai)
; #pragma unroll
;             for (int m = 0; m < 4; ++m) rsv[ai][m] = RS ? rs[row0 + ai * HALF + m * 16] : 1.0f;
; #pragma unroll
;         for (int ai = 0; ai < 2; ++ai)
; #pragma unroll
;             for (int m = 0; m < 4; ++m) { const int r = row0 + ai * HALF + m * 16;
;                 bf16_t* rowp = hm ? base + ((size_t)((r >> 12) * 8 + (colt >> 7)) * 4096 + (r & 4095)) * 128 + wc * 32 + 8 * fq : base + (size_t)r * ldc + col0;
;                 float rv = sc; if (RS == 1) rv *= rsv[ai][m]; if (RS == 2) rv *= __builtin_amdgcn_rsqf(rsv[ai][m] * (1.0f / DM) + EPS);
;     ...
;     const char* cA = g.a(cur); const char* cB = g.b(cur);
;     S.a_ready(cur);
;     PG8_STAGE(PG8_SB(0, 0), cB, voffB); PG8_STAGE(PG8_SB(0, 1), cB + hstepB, voffB); PG8_STAGE(PG8_SA(0, 0), cA, voffA); PG8_STAGE(PG8_SA(0, 1), cA + hstepA, voffA);
;     if (wr == 1) PG8_BAR;
;     PG8_WAIT_V(2); PG8_BAR;
;     PG8_STAGE(PG8_SB(1, 0), cB + kstep, voffB); PG8_STAGE(PG8_SA(1, 0), cA + kstep, voffA); PG8_STAGE(PG8_SB(1, 1), cB + hstepB + kstep, voffB);
.LBB0_703:
	v_readlane_b32 s0, v254, 40
	v_readlane_b32 s1, v254, 41
	s_and_b64 s[0:1], s[0:1], s[20:21]
	s_and_b64 s[0:1], s[0:1], exec
	v_readlane_b32 s0, v254, 20
	v_readlane_b32 s1, v254, 21
	s_cselect_b32 s77, s1, s69
	s_cselect_b32 s76, s0, s68
	s_lshl_b64 s[0:1], s[78:79], 12
	s_add_u32 s30, s74, s0
	s_mov_b32 s0, s70
	s_addc_u32 s31, s75, s1
	v_mbcnt_lo_u32_b32 v0, s0, 0
	v_mbcnt_hi_u32_b32 v0, s0, v0
	v_readlane_b32 s0, v254, 22
	v_readlane_b32 s1, v254, 23
	s_and_b64 vcc, exec, s[0:1]
	s_cbranch_vccnz .LBB0_723
	v_readlane_b32 s98, v254, 36
	v_readlane_b32 s99, v254, 37
	s_lshl_b64 s[100:101], s[78:79], 2
	s_add_u32 s98, s98, s100
	s_addc_u32 s99, s99, s101
	v_readlane_b32 s100, v255, 19
	s_lshl_b32 s100, s100, 8
	s_add_i32 s100, s100, s48
	v_and_or_b32 v248, v0, 15, s100
	v_mov_b32_e32 v249, 0
	v_lshl_add_u64 v[248:249], v[248:249], 2, s[98:99]
	global_load_dword v240, v[248:249], off
	global_load_dword v241, v[248:249], off offset:64
	global_load_dword v242, v[248:249], off offset:128
	global_load_dword v243, v[248:249], off offset:192
	global_load_dword v244, v[248:249], off offset:512
	global_load_dword v245, v[248:249], off offset:576
	global_load_dword v246, v[248:249], off offset:640
	global_load_dword v247, v[248:249], off offset:704
	v_mbcnt_lo_u32_b32 v250, -1, 0
	v_mbcnt_hi_u32_b32 v250, -1, v250
	v_and_b32_e32 v251, 15, v250
	v_lshrrev_b32_e32 v250, 4, v250
	v_lshlrev_b32_e32 v250, 4, v250
	v_lshl_or_b32 v250, v251, 14, v250
	v_lshlrev_b32_e32 v251, 2, v251
	v_lshl_add_u32 v1, v0, 4, s33
	v_ashrrev_i32_e32 v2, 31, v1
	v_lshrrev_b32_e32 v2, 22, v2
	v_add_u32_e32 v2, v1, v2
	v_ashrrev_i32_e32 v2, 10, v2
	v_mul_i32_i24_e32 v3, 0x400, v2
	v_sub_u32_e32 v3, v1, v3
	v_lshrrev_b32_e32 v4, 4, v3
	v_bitop3_b32 v3, v4, v3, 32 bitop3:0x6c
	v_ashrrev_i32_e32 v5, 31, v3
	v_lshrrev_b32_e32 v5, 26, v5
	v_lshlrev_b32_e32 v4, 3, v2
	v_add_u32_e32 v5, v3, v5
	v_and_b32_e32 v4, -16, v4
	v_ashrrev_i32_e32 v6, 6, v5
	v_and_b32_e32 v5, 0xc0, v5
	v_add_u32_e32 v4, v6, v4
	v_sub_u32_e32 v3, v3, v5
	v_lshlrev_b32_e32 v2, 5, v2
	v_ashrrev_i16_sdwa v3, v228, sext(v3) dst_sel:DWORD dst_unused:UNUSED_PAD src0_sel:DWORD src1_sel:BYTE_0
	v_lshlrev_b32_e32 v5, 1, v4
	v_lshrrev_b32_e32 v7, 2, v4
	v_and_b32_e32 v6, 3, v6
	s_mov_b32 s0, 0xfffe0
	v_and_b32_e32 v2, 32, v2
	v_bfe_i32 v3, v3, 0, 16
	v_and_b32_e32 v5, 24, v5
	v_and_b32_e32 v7, 4, v7
	v_and_or_b32 v6, v4, s0, v6
	v_or3_b32 v5, v6, v7, v5
	v_add_lshl_u32 v2, v2, v3, 1
	v_add_u32_e32 v1, 0x2000, v1
	v_lshl_add_u32 v128, v4, 12, v2
	v_lshl_add_u32 v192, v5, 12, v2
	v_ashrrev_i32_e32 v2, 31, v1
	v_lshrrev_b32_e32 v2, 22, v2
	v_add_u32_e32 v2, v1, v2
	v_ashrrev_i32_e32 v2, 10, v2
	v_mul_i32_i24_e32 v3, 0x400, v2
	v_sub_u32_e32 v1, v1, v3
	v_lshrrev_b32_e32 v3, 4, v1
	v_bitop3_b32 v1, v3, v1, 32 bitop3:0x6c
	v_ashrrev_i32_e32 v4, 31, v1
	v_lshrrev_b32_e32 v4, 26, v4
	v_add_u32_e32 v4, v1, v4
	v_ashrrev_i32_e32 v5, 6, v4
	v_and_b32_e32 v4, 0xffc0, v4
	v_sub_u32_e32 v1, v1, v4
	v_lshlrev_b32_e32 v3, 3, v2
	v_lshrrev_b16_e32 v4, 7, v1
	v_and_b32_e32 v3, -16, v3
	v_and_b32_e32 v4, 1, v4
	v_add_u32_e32 v3, v5, v3
	v_add_u16_e32 v1, v1, v4
	v_lshlrev_b32_e32 v2, 5, v2
	v_ashrrev_i16_sdwa v1, v228, sext(v1) dst_sel:DWORD dst_unused:UNUSED_PAD src0_sel:DWORD src1_sel:BYTE_0
	v_lshlrev_b32_e32 v4, 1, v3
	v_lshrrev_b32_e32 v6, 2, v3
	v_and_b32_e32 v5, 3, v5
	v_and_b32_e32 v2, 32, v2
	v_bfe_i32 v1, v1, 0, 16
	v_and_b32_e32 v4, 24, v4
	v_and_b32_e32 v6, 4, v6
	v_and_or_b32 v5, v3, s0, v5
	s_add_i32 s0, s33, 0
	v_readlane_b32 s20, v255, 25
	v_or3_b32 v4, v5, v6, v4
	v_add_lshl_u32 v1, v2, v1, 1
	s_add_i32 m0, s0, 0x10000
	v_readlane_b32 s21, v255, 26
	v_lshl_add_u32 v132, v4, 12, v1
	v_lshl_add_u32 v130, v3, 12, v1
	v_cmp_ne_u32_e64 s[38:39], 1, v226
	s_nop 1
	global_load_lds_dwordx4 v192, s[20:21]
	s_add_i32 m0, s0, 0x12000
	s_nop 0
	global_load_lds_dwordx4 v132, s[20:21]
	v_readlane_b32 s20, v255, 23
	s_add_i32 m0, s0, 0x14000
	v_readlane_b32 s21, v255, 24
	s_nop 4
	global_load_lds_dwordx4 v192, s[20:21]
	s_add_i32 m0, s0, 0x16000
	s_nop 0
	global_load_lds_dwordx4 v132, s[20:21]
	v_readlane_b32 s20, v255, 21
	v_readlane_b32 s21, v255, 22
	s_add_u32 s46, s30, s20
	s_addc_u32 s47, s31, s21
	s_add_i32 s1, s0, 0x2000
	s_mov_b32 m0, s0
	s_add_u32 s20, s46, 0x80000
	global_load_lds_dwordx4 v128, s[46:47]
	s_mov_b32 m0, s1
	s_addc_u32 s21, s47, 0
	s_add_i32 s34, s0, 0x4000
	global_load_lds_dwordx4 v130, s[46:47]
	s_mov_b32 m0, s34
	s_add_i32 s35, s0, 0x6000
	global_load_lds_dwordx4 v128, s[20:21]
	s_mov_b32 m0, s35
	s_nop 0
	global_load_lds_dwordx4 v130, s[20:21]
	v_readlane_b32 s98, v255, 25
	v_readlane_b32 s99, v255, 26
	s_add_u32 s98, s98, 0x80
	s_addc_u32 s99, s99, 0
	s_add_i32 m0, s0, 0x18000
	s_nop 0
	global_load_lds_dwordx4 v192, s[98:99]
	s_add_i32 m0, s0, 0x1a000
	s_nop 0
	global_load_lds_dwordx4 v132, s[98:99]
	s_add_u32 s98, s46, 0x80
	s_addc_u32 s99, s47, 0
	s_add_i32 m0, s0, 0x8000
	s_nop 0
	global_load_lds_dwordx4 v128, s[98:99]
	s_add_i32 m0, s0, 0xa000
	s_nop 0
	global_load_lds_dwordx4 v130, s[98:99]
	v_readlane_b32 s98, v255, 27
	v_readlane_b32 s99, v255, 28
	s_add_i32 m0, s0, 0x1c000
	s_nop 0
	global_load_lds_dwordx4 v192, s[98:99]
	s_add_i32 m0, s0, 0x1e000
	s_nop 0
	global_load_lds_dwordx4 v132, s[98:99]
	v_readlane_b32 s20, v254, 26
	v_readlane_b32 s21, v254, 27
	s_andn2_b64 vcc, exec, s[20:21]
	s_cbranch_vccnz .LBB0_706
	s_barrier

;     __device__ __forceinline__ const char* a(const Unit& u) const { return (const char*)A + (size_t)u.pm * 2 * hA(); }
;     __device__ __forceinline__ const char* b(const Unit& u) const { return (const char*)Bt + (size_t)u.pn * 2 * hB() + (size_t)(u.pm >> gshift) * goff; }
;     __device__ __forceinline__ const char* a(const Unit& u) const { return (const char*)A + (size_t)u.pm * 2 * hA(); }
;     __host__ __device__ bool next(int i, Unit& u) const {
;         const long L = (long)i * G + c; if (L >= nwg) return false;
;         int wgid = (int)L; { const int q = nwg / NXCD, r = nwg % NXCD, xcd = wgid % NXCD, off = wgid / NXCD; wgid = (xcd < r ? xcd * (q + 1) : r * (q + 1) + (xcd - r) * q) + off; }
;         const int nig = wgm * nN, gid = wgid / nig, fm = gid * wgm, gsz = (nM - fm) < wgm ? (nM - fm) : wgm;
;         u.pm = fm + ((wgid % nig) % gsz); u.pn = (wgid % nig) / gsz; return true;
;     __device__ __forceinline__ void operator()(const f32x4 (&acc)[2][2][4][2], const Unit& u, int wr, int wc, int fr, int fq) const {
;     ...
;             for (int m = 0; m < 4; ++m) { const int r = row0 + ai * HALF + m * 16;
;                 bf16_t* rowp = hm ? base + ((size_t)((r >> 12) * 8 + (colt >> 7)) * 4096 + (r & 4095)) * 128 + wc * 32 + 8 * fq : base + (size_t)r * ldc + col0;
;                 float rv = sc; if (RS == 1) rv *= rsv[ai][m]; if (RS == 2) rv *= __builtin_amdgcn_rsqf(rsv[ai][m] * (1.0f / DM) + EPS);
; #pragma unroll
;                 for (int bj = 0; bj < 2; ++bj) { f32x4 v0 = acc[ai][bj][m][0] * rv, v1 = acc[ai][bj][m][1] * rv;
;                     if (CS) { v0 = v0 * cv[bj][0]; v1 = v1 * cv[bj][1]; }
;                     if (ACT == 2) {
; #pragma unroll
;                         for (int e = 0; e < 4; ++e) { float a = v0[e] > 0.f ? v0[e] : 0.f, b = v1[e] > 0.f ? v1[e] : 0.f; v0[e] = a * a; v1[e] = b * b; } }
;                     if (k8) {
;                         u32x2 w8; w8.x = pk_fp8x4(v0); w8.y = pk_fp8x4(v1);
;                         *(u32x2*)((unsigned char*)base + ((size_t)((r >> 12) * 8 + (colt >> 7) + bj) * 4096 + (r & 4095)) * 128 + wc * 32 + 8 * fq) = w8;
;                     } else {
;                     u32x4 w; w.x = cvt_pk_bf16(v0[0], v0[1]); w.y = cvt_pk_bf16(v0[2], v0[3]); w.z = cvt_pk_bf16(v1[0], v1[1]); w.w = cvt_pk_bf16(v1[2], v1[3]);
;                     *(u32x4*)(rowp + bj * bstep) = w; } } }
.LBB0_714:
	s_ashr_i32 s20, s23, 3
	s_add_i32 s20, s28, s20
	s_ashr_i32 s21, s20, 31
	s_lshr_b32 s21, s21, 25
	s_add_i32 s21, s20, s21
	s_ashr_i32 s22, s21, 7
	s_lshl_b32 s22, s22, 2
	s_sub_i32 s23, 32, s22
	s_min_i32 s23, s23, 4
	s_abs_i32 s28, s23
	v_cvt_f32_u32_e32 v249, s28
	s_sub_i32 s36, 0, s28
	s_and_b32 s21, s21, 0xffffff80
	s_sub_i32 s21, s20, s21
	v_rcp_iflag_f32_e32 v249, v249
	s_abs_i32 s20, s21
	s_xor_b32 s29, s21, s23
	s_ashr_i32 s29, s29, 31
	v_mul_f32_e32 v249, 0x4f7ffffe, v249
	v_cvt_u32_f32_e32 v249, v249
	s_nop 0
	v_readfirstlane_b32 s37, v249
	s_mul_i32 s36, s36, s37
	s_mul_hi_u32 s36, s37, s36
	s_add_i32 s37, s37, s36
	s_mul_hi_u32 s36, s20, s37
	s_mul_i32 s37, s36, s28
	s_sub_i32 s20, s20, s37
	s_add_i32 s42, s36, 1
	s_sub_i32 s37, s20, s28
	s_cmp_ge_u32 s20, s28
	s_cselect_b32 s36, s42, s36
	s_cselect_b32 s20, s37, s20
	s_add_i32 s37, s36, 1
	s_cmp_ge_u32 s20, s28
	s_cselect_b32 s20, s37, s36
	s_xor_b32 s20, s20, s29
	s_sub_i32 s20, s20, s29
	s_mul_i32 s23, s20, s23
	s_sub_i32 s21, s21, s23
	s_add_i32 s36, s22, s21
.LBB0_715:
	s_ashr_i32 s37, s36, 31
	s_lshl_b64 s[22:23], s[36:37], 20
	s_add_u32 s42, s30, s22
	s_addc_u32 s43, s31, s23
	s_and_b64 s[22:23], s[40:41], exec
	s_cselect_b32 s37, s43, s47
	s_cselect_b32 vcc_lo, s42, s46
	s_ashr_i32 s21, s20, 31
	s_lshl_b64 s[22:23], s[20:21], 20
	s_add_u32 s44, s64, s22
	s_addc_u32 s45, s65, s23
	s_and_b64 s[22:23], s[40:41], exec
	s_cselect_b32 s21, s45, s27
	s_cselect_b32 s86, s44, s26
	s_add_u32 s87, s26, 0x100
	s_addc_u32 s88, s27, 0
	s_mov_b32 s89, -2
	s_cmp_lt_u32 s73, 2
	s_cbranch_scc1 mk_zero_p5
	s_add_u32 s80, s46, 0x100
	s_addc_u32 s81, s47, 0
	s_cmp_eq_u32 s89, 28
	s_cselect_b32 s28, vcc_lo, s80
	s_cselect_b32 s29, s37, s81
	s_cselect_b32 s23, s21, s88
	s_cselect_b32 s22, s86, s87
	s_add_u32 s26, s28, 0x80
	s_addc_u32 s27, s29, 0
	s_add_u32 s66, s22, 0x80
	s_addc_u32 s67, s23, 0
	s_add_u32 s90, s46, 0x80080
	s_addc_u32 s91, s47, 0
	s_add_u32 s52, s28, 0x80000
	s_addc_u32 s53, s29, 0
	s_add_u32 s56, s22, 0x80000
	s_addc_u32 s57, s23, 0
	s_add_u32 s46, s22, 0x80080
	s_addc_u32 s47, s23, 0
	s_add_i32 s92, 0, 0x10000
	v_add_u32_e32 v133, s92, v129
	s_add_i32 s93, 0, 0x14000
	ds_read_b128 v[134:137], v133
	ds_read_b128 v[138:141], v133 offset:1024
	ds_read_b128 v[142:145], v133 offset:2048
	ds_read_b128 v[146:149], v133 offset:3072
	v_add_u32_e32 v133, s93, v129
	ds_read_b128 v[150:153], v133
	ds_read_b128 v[154:157], v133 offset:1024
	ds_read_b128 v[158:161], v133 offset:2048
	ds_read_b128 v[162:165], v133 offset:3072
	s_add_i32 m0, s0, 0xc000
	ds_read_b128 v[166:169], v131
	ds_read_b128 v[170:173], v131 offset:1024
	ds_read_b128 v[174:177], v131 offset:2048
	ds_read_b128 v[178:181], v131 offset:3072
	ds_read_b128 v[182:185], v131 offset:4096
	ds_read_b128 v[186:189], v131 offset:5120
	ds_read_b128 v[202:205], v131 offset:6144
	ds_read_b128 v[206:209], v131 offset:7168
	global_load_lds_dwordx4 v128, s[90:91]
	s_add_i32 m0, s0, 0xe000
	s_nop 0
	global_load_lds_dwordx4 v130, s[90:91]
	v_fmamk_f32 v248, v244, 0x3a000000, v227
	v_rsq_f32_e32 v248, v248
	s_nop 0
	v_pk_mul_f32 v[56:57], v[56:57], v[248:249] op_sel_hi:[1,0]
	v_pk_mul_f32 v[58:59], v[58:59], v[248:249] op_sel_hi:[1,0]
	v_pk_mul_f32 v[60:61], v[60:61], v[248:249] op_sel_hi:[1,0]
	v_pk_mul_f32 v[62:63], v[62:63], v[248:249] op_sel_hi:[1,0]
	v_max_f32_e32 v56, 0, v56
	v_max_f32_e32 v57, 0, v57
	v_max_f32_e32 v58, 0, v58
	v_max_f32_e32 v59, 0, v59
	v_max_f32_e32 v60, 0, v60
	v_max_f32_e32 v61, 0, v61
	v_max_f32_e32 v62, 0, v62
	v_max_f32_e32 v63, 0, v63
	v_pk_mul_f32 v[56:57], v[56:57], v[56:57]
	v_pk_mul_f32 v[58:59], v[58:59], v[58:59]
	v_pk_mul_f32 v[60:61], v[60:61], v[60:61]
	v_pk_mul_f32 v[62:63], v[62:63], v[62:63]
	v_cvt_pk_bf16_f32 v60, v60, v61
	v_cvt_pk_bf16_f32 v61, v62, v63
	v_cvt_pk_bf16_f32 v62, v56, v57
	v_cvt_pk_bf16_f32 v63, v58, v59
	global_store_dwordx4 v250, v[60:63], s[100:101]
	v_pk_mul_f32 v[48:49], v[48:49], v[248:249] op_sel_hi:[1,0]
	v_pk_mul_f32 v[50:51], v[50:51], v[248:249] op_sel_hi:[1,0]
	v_pk_mul_f32 v[52:53], v[52:53], v[248:249] op_sel_hi:[1,0]
	v_pk_mul_f32 v[54:55], v[54:55], v[248:249] op_sel_hi:[1,0]
	v_max_f32_e32 v48, 0, v48
	v_max_f32_e32 v49, 0, v49
	v_max_f32_e32 v50, 0, v50
	v_max_f32_e32 v51, 0, v51
	v_max_f32_e32 v52, 0, v52
	v_max_f32_e32 v53, 0, v53
	v_max_f32_e32 v54, 0, v54
	v_max_f32_e32 v55, 0, v55
	v_pk_mul_f32 v[48:49], v[48:49], v[48:49]
	v_pk_mul_f32 v[50:51], v[50:51], v[50:51]
	v_pk_mul_f32 v[52:53], v[52:53], v[52:53]
	v_pk_mul_f32 v[54:55], v[54:55], v[54:55]
	v_cvt_pk_bf16_f32 v52, v52, v53
	v_cvt_pk_bf16_f32 v53, v54, v55
	v_cvt_pk_bf16_f32 v54, v48, v49
	v_cvt_pk_bf16_f32 v55, v50, v51
	global_store_dwordx4 v250, v[52:55], s[100:101] offset:256
	s_add_u32 s100, s100, 0x40000
	s_addc_u32 s101, s101, 0
	v_fmamk_f32 v248, v245, 0x3a000000, v227
	v_rsq_f32_e32 v248, v248
	s_nop 0
	v_pk_mul_f32 v[40:41], v[40:41], v[248:249] op_sel_hi:[1,0]
	v_pk_mul_f32 v[42:43], v[42:43], v[248:249] op_sel_hi:[1,0]
	v_pk_mul_f32 v[44:45], v[44:45], v[248:249] op_sel_hi:[1,0]
	v_pk_mul_f32 v[46:47], v[46:47], v[248:249] op_sel_hi:[1,0]
	v_max_f32_e32 v40, 0, v40
	v_max_f32_e32 v41, 0, v41
	v_max_f32_e32 v42, 0, v42
	v_max_f32_e32 v43, 0, v43
	v_max_f32_e32 v44, 0, v44
	v_max_f32_e32 v45, 0, v45
	v_max_f32_e32 v46, 0, v46
	v_max_f32_e32 v47, 0, v47
	v_pk_mul_f32 v[40:41], v[40:41], v[40:41]
	v_pk_mul_f32 v[42:43], v[42:43], v[42:43]
	v_pk_mul_f32 v[44:45], v[44:45], v[44:45]
	v_pk_mul_f32 v[46:47], v[46:47], v[46:47]
	v_cvt_pk_bf16_f32 v44, v44, v45
	v_cvt_pk_bf16_f32 v45, v46, v47
	v_cvt_pk_bf16_f32 v46, v40, v41
	v_cvt_pk_bf16_f32 v47, v42, v43
	global_store_dwordx4 v250, v[44:47], s[100:101]
	v_pk_mul_f32 v[32:33], v[32:33], v[248:249] op_sel_hi:[1,0]
	v_pk_mul_f32 v[34:35], v[34:35], v[248:249] op_sel_hi:[1,0]
	v_pk_mul_f32 v[36:37], v[36:37], v[248:249] op_sel_hi:[1,0]
	v_pk_mul_f32 v[38:39], v[38:39], v[248:249] op_sel_hi:[1,0]
	v_max_f32_e32 v32, 0, v32
	v_max_f32_e32 v33, 0, v33
	v_max_f32_e32 v34, 0, v34
	v_max_f32_e32 v35, 0, v35
	v_max_f32_e32 v36, 0, v36
	v_max_f32_e32 v37, 0, v37
	v_max_f32_e32 v38, 0, v38
	v_max_f32_e32 v39, 0, v39
	v_pk_mul_f32 v[32:33], v[32:33], v[32:33]
	v_pk_mul_f32 v[34:35], v[34:35], v[34:35]
	v_pk_mul_f32 v[36:37], v[36:37], v[36:37]
	v_pk_mul_f32 v[38:39], v[38:39], v[38:39]
	v_cvt_pk_bf16_f32 v36, v36, v37
	v_cvt_pk_bf16_f32 v37, v38, v39
	v_cvt_pk_bf16_f32 v38, v32, v33
	v_cvt_pk_bf16_f32 v39, v34, v35
	global_store_dwordx4 v250, v[36:39], s[100:101] offset:256
	s_add_u32 s100, s100, 0x40000
	s_addc_u32 s101, s101, 0
	s_waitcnt vmcnt(20)
	s_waitcnt lgkmcnt(0)
	s_barrier
;     __device__ __forceinline__ const char* a(const Unit& u) const { return (const char*)A + (size_t)u.pm * 2 * hA(); }
;     __device__ __forceinline__ const char* b(const Unit& u) const { return (const char*)Bt + (size_t)u.pn * 2 * hB() + (size_t)(u.pm >> gshift) * goff; }
;     __device__ __forceinline__ const char* a(const Unit& u) const { return (const char*)A + (size_t)u.pm * 2 * hA(); }
;     __device__ __forceinline__ const char* b(const Unit& u) const { return (const char*)Bt + (size_t)((u.pn >> 4) * 4096 + (u.pn & 15) * 16) * 1024 * 2 + (size_t)(u.pm >> 1) * 512; }
;     __device__ __forceinline__ const char* a(const Unit&) const { return (const char*)A; }
;     __device__ __forceinline__ const char* b(const Unit& u) const { return (const char*)Bt + ((size_t)(((u.pm >> 4) * 1024 + u.pn * 256) * 16 + (u.pm & 15)) * 512) * 2; }
;     __device__ __forceinline__ void operator()(const f32x4 (&acc)[2][2][4][2], const Unit& u, int wr, int wc, int fr, int fq) const {
;     ...
;             for (int m = 0; m < 4; ++m) { const int r = row0 + ai * HALF + m * 16;
;                 bf16_t* rowp = hm ? base + ((size_t)((r >> 12) * 8 + (colt >> 7)) * 4096 + (r & 4095)) * 128 + wc * 32 + 8 * fq : base + (size_t)r * ldc + col0;
;                 float rv = sc; if (RS == 1) rv *= rsv[ai][m]; if (RS == 2) rv *= __builtin_amdgcn_rsqf(rsv[ai][m] * (1.0f / DM) + EPS);
; #pragma unroll
;                 for (int bj = 0; bj < 2; ++bj) { f32x4 v0 = acc[ai][bj][m][0] * rv, v1 = acc[ai][bj][m][1] * rv;
;                     if (CS) { v0 = v0 * cv[bj][0]; v1 = v1 * cv[bj][1]; }
;                     if (ACT == 2) {
; #pragma unroll
;                         for (int e = 0; e < 4; ++e) { float a = v0[e] > 0.f ? v0[e] : 0.f, b = v1[e] > 0.f ? v1[e] : 0.f; v0[e] = a * a; v1[e] = b * b; } }
;                     if (k8) {
;                         u32x2 w8; w8.x = pk_fp8x4(v0); w8.y = pk_fp8x4(v1);
;                         *(u32x2*)((unsigned char*)base + ((size_t)((r >> 12) * 8 + (colt >> 7) + bj) * 4096 + (r & 4095)) * 128 + wc * 32 + 8 * fq) = w8;
;                     } else {
;                     u32x4 w; w.x = cvt_pk_bf16(v0[0], v0[1]); w.y = cvt_pk_bf16(v0[2], v0[3]); w.z = cvt_pk_bf16(v1[0], v1[1]); w.w = cvt_pk_bf16(v1[2], v1[3]);
;                     *(u32x4*)(rowp + bj * bstep) = w; } } }
	s_setprio 1
	s_waitcnt lgkmcnt(0)
	v_mfma_f32_16x16x32_bf16 v[124:127], v[134:137], v[166:169], 0
	v_fmamk_f32 v248, v246, 0x3a000000, v227
	v_rsq_f32_e32 v248, v248
	s_nop 0
	v_mfma_f32_16x16x32_bf16 v[120:123], v[142:145], v[166:169], 0
	v_pk_mul_f32 v[24:25], v[24:25], v[248:249] op_sel_hi:[1,0]
	v_pk_mul_f32 v[26:27], v[26:27], v[248:249] op_sel_hi:[1,0]
	v_pk_mul_f32 v[28:29], v[28:29], v[248:249] op_sel_hi:[1,0]
	v_mfma_f32_16x16x32_bf16 v[108:111], v[134:137], v[174:177], 0
	v_pk_mul_f32 v[30:31], v[30:31], v[248:249] op_sel_hi:[1,0]
	v_max_f32_e32 v24, 0, v24
	v_max_f32_e32 v25, 0, v25
	v_mfma_f32_16x16x32_bf16 v[104:107], v[142:145], v[174:177], 0
	v_max_f32_e32 v26, 0, v26
	v_max_f32_e32 v27, 0, v27
	v_max_f32_e32 v28, 0, v28
	v_mfma_f32_16x16x32_bf16 v[92:95], v[134:137], v[182:185], 0
	v_max_f32_e32 v29, 0, v29
	v_max_f32_e32 v30, 0, v30
	v_max_f32_e32 v31, 0, v31
	v_mfma_f32_16x16x32_bf16 v[88:91], v[142:145], v[182:185], 0
	v_pk_mul_f32 v[24:25], v[24:25], v[24:25]
	v_pk_mul_f32 v[26:27], v[26:27], v[26:27]
	v_pk_mul_f32 v[28:29], v[28:29], v[28:29]
	v_mfma_f32_16x16x32_bf16 v[76:79], v[134:137], v[202:205], 0
	v_pk_mul_f32 v[30:31], v[30:31], v[30:31]
	v_cvt_pk_bf16_f32 v28, v28, v29
	v_cvt_pk_bf16_f32 v29, v30, v31
	v_mfma_f32_16x16x32_bf16 v[72:75], v[142:145], v[202:205], 0
	v_cvt_pk_bf16_f32 v30, v24, v25
	v_cvt_pk_bf16_f32 v31, v26, v27
	global_store_dwordx4 v250, v[28:31], s[100:101]
	v_mfma_f32_16x16x32_bf16 v[124:127], v[138:141], v[170:173], v[124:127]
	v_pk_mul_f32 v[16:17], v[16:17], v[248:249] op_sel_hi:[1,0]
	v_pk_mul_f32 v[18:19], v[18:19], v[248:249] op_sel_hi:[1,0]
	v_pk_mul_f32 v[20:21], v[20:21], v[248:249] op_sel_hi:[1,0]
	v_mfma_f32_16x16x32_bf16 v[120:123], v[146:149], v[170:173], v[120:123]
	v_pk_mul_f32 v[22:23], v[22:23], v[248:249] op_sel_hi:[1,0]
	v_max_f32_e32 v16, 0, v16
	v_max_f32_e32 v17, 0, v17
	v_mfma_f32_16x16x32_bf16 v[108:111], v[138:141], v[178:181], v[108:111]
	v_max_f32_e32 v18, 0, v18
	v_max_f32_e32 v19, 0, v19
	v_max_f32_e32 v20, 0, v20
	v_mfma_f32_16x16x32_bf16 v[104:107], v[146:149], v[178:181], v[104:107]
	v_max_f32_e32 v21, 0, v21
	v_max_f32_e32 v22, 0, v22
	v_max_f32_e32 v23, 0, v23
	v_mfma_f32_16x16x32_bf16 v[92:95], v[138:141], v[186:189], v[92:95]
	v_pk_mul_f32 v[16:17], v[16:17], v[16:17]
	v_pk_mul_f32 v[18:19], v[18:19], v[18:19]
	v_pk_mul_f32 v[20:21], v[20:21], v[20:21]
	v_mfma_f32_16x16x32_bf16 v[88:91], v[146:149], v[186:189], v[88:91]
	v_pk_mul_f32 v[22:23], v[22:23], v[22:23]
	v_cvt_pk_bf16_f32 v20, v20, v21
	v_cvt_pk_bf16_f32 v21, v22, v23
	v_mfma_f32_16x16x32_bf16 v[76:79], v[138:141], v[206:209], v[76:79]
	v_cvt_pk_bf16_f32 v22, v16, v17
	v_cvt_pk_bf16_f32 v23, v18, v19
	global_store_dwordx4 v250, v[20:23], s[100:101] offset:256
	v_mfma_f32_16x16x32_bf16 v[72:75], v[146:149], v[206:209], v[72:75]
	s_add_u32 s100, s100, 0x40000
	s_addc_u32 s101, s101, 0
	v_fmamk_f32 v248, v247, 0x3a000000, v227
	s_setprio 0
	s_setprio 1
	v_mfma_f32_16x16x32_bf16 v[116:119], v[150:153], v[166:169], 0
	v_rsq_f32_e32 v248, v248
	s_nop 0
	v_pk_mul_f32 v[8:9], v[8:9], v[248:249] op_sel_hi:[1,0]
	v_mfma_f32_16x16x32_bf16 v[112:115], v[158:161], v[166:169], 0
	v_pk_mul_f32 v[10:11], v[10:11], v[248:249] op_sel_hi:[1,0]
	v_pk_mul_f32 v[12:13], v[12:13], v[248:249] op_sel_hi:[1,0]
	v_pk_mul_f32 v[14:15], v[14:15], v[248:249] op_sel_hi:[1,0]
	v_mfma_f32_16x16x32_bf16 v[100:103], v[150:153], v[174:177], 0
	v_max_f32_e32 v8, 0, v8
	v_max_f32_e32 v9, 0, v9
	v_max_f32_e32 v10, 0, v10
	v_mfma_f32_16x16x32_bf16 v[96:99], v[158:161], v[174:177], 0
	v_max_f32_e32 v11, 0, v11
	v_max_f32_e32 v12, 0, v12
	v_max_f32_e32 v13, 0, v13
	v_mfma_f32_16x16x32_bf16 v[84:87], v[150:153], v[182:185], 0
	v_max_f32_e32 v14, 0, v14
	v_max_f32_e32 v15, 0, v15
	v_pk_mul_f32 v[8:9], v[8:9], v[8:9]
	v_mfma_f32_16x16x32_bf16 v[80:83], v[158:161], v[182:185], 0
	v_pk_mul_f32 v[10:11], v[10:11], v[10:11]
	v_pk_mul_f32 v[12:13], v[12:13], v[12:13]
	v_pk_mul_f32 v[14:15], v[14:15], v[14:15]
	v_mfma_f32_16x16x32_bf16 v[68:71], v[150:153], v[202:205], 0
	v_cvt_pk_bf16_f32 v12, v12, v13
	v_cvt_pk_bf16_f32 v13, v14, v15
	v_cvt_pk_bf16_f32 v14, v8, v9
	v_mfma_f32_16x16x32_bf16 v[64:67], v[158:161], v[202:205], 0
	v_cvt_pk_bf16_f32 v15, v10, v11
	global_store_dwordx4 v250, v[12:15], s[100:101]
	v_pk_mul_f32 v[0:1], v[0:1], v[248:249] op_sel_hi:[1,0]
	v_mfma_f32_16x16x32_bf16 v[116:119], v[154:157], v[170:173], v[116:119]
	v_pk_mul_f32 v[2:3], v[2:3], v[248:249] op_sel_hi:[1,0]
	v_pk_mul_f32 v[4:5], v[4:5], v[248:249] op_sel_hi:[1,0]
	v_pk_mul_f32 v[6:7], v[6:7], v[248:249] op_sel_hi:[1,0]
	v_mfma_f32_16x16x32_bf16 v[112:115], v[162:165], v[170:173], v[112:115]
	v_max_f32_e32 v0, 0, v0
	v_max_f32_e32 v1, 0, v1
	v_max_f32_e32 v2, 0, v2
	v_mfma_f32_16x16x32_bf16 v[100:103], v[154:157], v[178:181], v[100:103]
	v_max_f32_e32 v3, 0, v3
	v_max_f32_e32 v4, 0, v4
	v_max_f32_e32 v5, 0, v5
	v_mfma_f32_16x16x32_bf16 v[96:99], v[162:165], v[178:181], v[96:99]
	v_max_f32_e32 v6, 0, v6
	v_max_f32_e32 v7, 0, v7
	v_pk_mul_f32 v[0:1], v[0:1], v[0:1]
	v_mfma_f32_16x16x32_bf16 v[84:87], v[154:157], v[186:189], v[84:87]
	v_pk_mul_f32 v[2:3], v[2:3], v[2:3]
	v_pk_mul_f32 v[4:5], v[4:5], v[4:5]
	v_pk_mul_f32 v[6:7], v[6:7], v[6:7]
	v_mfma_f32_16x16x32_bf16 v[80:83], v[162:165], v[186:189], v[80:83]
	v_cvt_pk_bf16_f32 v4, v4, v5
	v_cvt_pk_bf16_f32 v5, v6, v7
	v_cvt_pk_bf16_f32 v6, v0, v1
	v_mfma_f32_16x16x32_bf16 v[68:71], v[154:157], v[206:209], v[68:71]
	v_cvt_pk_bf16_f32 v7, v2, v3
	global_store_dwordx4 v250, v[4:7], s[100:101] offset:256
	s_add_u32 s100, s100, 0x40000
	v_mfma_f32_16x16x32_bf16 v[64:67], v[162:165], v[206:209], v[64:67]
	s_addc_u32 s101, s101, 0
	s_lshl_b32 s98, s74, 8
	s_add_i32 s98, s98, s48
	s_lshl_b32 s98, s98, 2
	v_add_u32_e32 v249, s98, v251
	global_load_dword v240, v249, s[24:25]
	global_load_dword v241, v249, s[24:25] offset:64
	global_load_dword v242, v249, s[24:25] offset:128
	global_load_dword v243, v249, s[24:25] offset:192
	global_load_dword v244, v249, s[24:25] offset:512
	global_load_dword v245, v249, s[24:25] offset:576
	global_load_dword v246, v249, s[24:25] offset:640
	global_load_dword v247, v249, s[24:25] offset:704
	s_setprio 0
	s_barrier
	s_add_i32 s90, s92, s33
	s_mov_b32 m0, s90
	ds_read_b128 v[166:169], v131 offset:16384
	ds_read_b128 v[170:173], v131 offset:17408
	ds_read_b128 v[174:177], v131 offset:18432
	ds_read_b128 v[178:181], v131 offset:19456
	ds_read_b128 v[182:185], v131 offset:20480
	ds_read_b128 v[186:189], v131 offset:21504
	ds_read_b128 v[202:205], v131 offset:22528
	ds_read_b128 v[206:209], v131 offset:23552
	global_load_lds_dwordx4 v192, s[22:23]
	s_add_i32 m0, s90, 0x2000
	s_nop 0
	global_load_lds_dwordx4 v132, s[22:23]
	s_add_i32 s22, s93, s33
	s_mov_b32 m0, s22
	s_nop 0
	global_load_lds_dwordx4 v192, s[56:57]
	s_add_i32 m0, s22, 0x2000
	s_nop 0
	global_load_lds_dwordx4 v132, s[56:57]
	s_mov_b32 m0, s0
	s_nop 0
	global_load_lds_dwordx4 v128, s[28:29]
	s_mov_b32 m0, s1
	s_nop 0
	global_load_lds_dwordx4 v130, s[28:29]
	s_waitcnt vmcnt(32)
	s_waitcnt lgkmcnt(0)
	s_barrier
	s_setprio 1
	s_waitcnt lgkmcnt(0)
	v_mfma_f32_16x16x32_bf16 v[60:63], v[134:137], v[166:169], 0
	v_mfma_f32_16x16x32_bf16 v[56:59], v[142:145], v[166:169], 0
	v_mfma_f32_16x16x32_bf16 v[44:47], v[134:137], v[174:177], 0
	v_mfma_f32_16x16x32_bf16 v[40:43], v[142:145], v[174:177], 0
	v_mfma_f32_16x16x32_bf16 v[28:31], v[134:137], v[182:185], 0
	v_mfma_f32_16x16x32_bf16 v[24:27], v[142:145], v[182:185], 0
	v_mfma_f32_16x16x32_bf16 v[12:15], v[134:137], v[202:205], 0
	v_mfma_f32_16x16x32_bf16 v[8:11], v[142:145], v[202:205], 0
	v_mfma_f32_16x16x32_bf16 v[60:63], v[138:141], v[170:173], v[60:63]
	v_mfma_f32_16x16x32_bf16 v[56:59], v[146:149], v[170:173], v[56:59]
	v_mfma_f32_16x16x32_bf16 v[44:47], v[138:141], v[178:181], v[44:47]
	v_mfma_f32_16x16x32_bf16 v[40:43], v[146:149], v[178:181], v[40:43]
	v_mfma_f32_16x16x32_bf16 v[28:31], v[138:141], v[186:189], v[28:31]
	v_mfma_f32_16x16x32_bf16 v[24:27], v[146:149], v[186:189], v[24:27]
	v_mfma_f32_16x16x32_bf16 v[12:15], v[138:141], v[206:209], v[12:15]
	v_mfma_f32_16x16x32_bf16 v[8:11], v[146:149], v[206:209], v[8:11]
	s_setprio 0
	s_setprio 1
	v_mfma_f32_16x16x32_bf16 v[52:55], v[150:153], v[166:169], 0
	v_mfma_f32_16x16x32_bf16 v[48:51], v[158:161], v[166:169], 0
	v_mfma_f32_16x16x32_bf16 v[36:39], v[150:153], v[174:177], 0
	v_mfma_f32_16x16x32_bf16 v[32:35], v[158:161], v[174:177], 0
	v_mfma_f32_16x16x32_bf16 v[20:23], v[150:153], v[182:185], 0
	v_mfma_f32_16x16x32_bf16 v[16:19], v[158:161], v[182:185], 0
	v_mfma_f32_16x16x32_bf16 v[4:7], v[150:153], v[202:205], 0
	v_mfma_f32_16x16x32_bf16 v[0:3], v[158:161], v[202:205], 0
	v_mfma_f32_16x16x32_bf16 v[52:55], v[154:157], v[170:173], v[52:55]
	v_mfma_f32_16x16x32_bf16 v[48:51], v[162:165], v[170:173], v[48:51]
	v_mfma_f32_16x16x32_bf16 v[36:39], v[154:157], v[178:181], v[36:39]
	v_mfma_f32_16x16x32_bf16 v[32:35], v[162:165], v[178:181], v[32:35]
	v_mfma_f32_16x16x32_bf16 v[20:23], v[154:157], v[186:189], v[20:23]
	v_mfma_f32_16x16x32_bf16 v[16:19], v[162:165], v[186:189], v[16:19]
	v_mfma_f32_16x16x32_bf16 v[4:7], v[154:157], v[206:209], v[4:7]
	v_mfma_f32_16x16x32_bf16 v[0:3], v[162:165], v[206:209], v[0:3]
	s_setprio 0
	s_barrier
	s_add_i32 s22, 0, 0x18000
	v_add_u32_e32 v133, s22, v129
	s_add_i32 s23, 0, 0x1c000
	ds_read_b128 v[134:137], v133
	ds_read_b128 v[138:141], v133 offset:1024
	ds_read_b128 v[142:145], v133 offset:2048
	ds_read_b128 v[146:149], v133 offset:3072
	v_add_u32_e32 v133, s23, v129
	ds_read_b128 v[150:153], v133
	ds_read_b128 v[154:157], v133 offset:1024
	ds_read_b128 v[158:161], v133 offset:2048
	ds_read_b128 v[162:165], v133 offset:3072
	s_mov_b32 m0, s34
	ds_read_b128 v[166:169], v131 offset:32768
	ds_read_b128 v[170:173], v131 offset:33792
	ds_read_b128 v[174:177], v131 offset:34816
	ds_read_b128 v[178:181], v131 offset:35840
	ds_read_b128 v[182:185], v131 offset:36864
	ds_read_b128 v[186:189], v131 offset:37888
	ds_read_b128 v[202:205], v131 offset:38912
	ds_read_b128 v[206:209], v131 offset:39936
	global_load_lds_dwordx4 v128, s[52:53]
	s_mov_b32 m0, s35
	s_nop 0
	global_load_lds_dwordx4 v130, s[52:53]
	s_waitcnt vmcnt(24)
	s_waitcnt lgkmcnt(0)
	s_barrier
; #define PG8_MMA(ai, bj, At, Bt) do { __builtin_amdgcn_s_setprio(1); _Pragma("unroll") for (int m = 0; m < 4; ++m) _Pragma("unroll") for (int n = 0; n < 2; ++n) _Pragma("unroll") for (int k = 0; k < 2; ++k) \
;         acc[ai][bj][m][n] = __builtin_amdgcn_mfma_f32_16x16x32_bf16(Bt[n][k], At[m][k], acc[ai][bj][m][n], 0, 0, 0); __builtin_amdgcn_s_setprio(0); } while (0)
;     ...
;         { const int tmid = (TSW > 0 && TSW < nt) ? TSW : nt;
;           _Pragma("unroll 1") for (int t = 0; t < tmid; t += 2) { PG8_BODY(PG8_MMA) }
	s_setprio 1
	s_waitcnt lgkmcnt(0)
	v_mfma_f32_16x16x32_bf16 v[124:127], v[134:137], v[166:169], v[124:127]
	v_mfma_f32_16x16x32_bf16 v[120:123], v[142:145], v[166:169], v[120:123]
	v_mfma_f32_16x16x32_bf16 v[108:111], v[134:137], v[174:177], v[108:111]
	v_mfma_f32_16x16x32_bf16 v[104:107], v[142:145], v[174:177], v[104:107]
	v_mfma_f32_16x16x32_bf16 v[92:95], v[134:137], v[182:185], v[92:95]
	v_mfma_f32_16x16x32_bf16 v[88:91], v[142:145], v[182:185], v[88:91]
	v_mfma_f32_16x16x32_bf16 v[76:79], v[134:137], v[202:205], v[76:79]
	v_mfma_f32_16x16x32_bf16 v[72:75], v[142:145], v[202:205], v[72:75]
	v_mfma_f32_16x16x32_bf16 v[124:127], v[138:141], v[170:173], v[124:127]
	v_mfma_f32_16x16x32_bf16 v[120:123], v[146:149], v[170:173], v[120:123]
	v_mfma_f32_16x16x32_bf16 v[108:111], v[138:141], v[178:181], v[108:111]
	v_mfma_f32_16x16x32_bf16 v[104:107], v[146:149], v[178:181], v[104:107]
	v_mfma_f32_16x16x32_bf16 v[92:95], v[138:141], v[186:189], v[92:95]
	v_mfma_f32_16x16x32_bf16 v[88:91], v[146:149], v[186:189], v[88:91]
	v_mfma_f32_16x16x32_bf16 v[76:79], v[138:141], v[206:209], v[76:79]
	v_mfma_f32_16x16x32_bf16 v[72:75], v[146:149], v[206:209], v[72:75]
	s_setprio 0
	s_setprio 1
	v_mfma_f32_16x16x32_bf16 v[116:119], v[150:153], v[166:169], v[116:119]
	v_mfma_f32_16x16x32_bf16 v[112:115], v[158:161], v[166:169], v[112:115]
	v_mfma_f32_16x16x32_bf16 v[100:103], v[150:153], v[174:177], v[100:103]
	v_mfma_f32_16x16x32_bf16 v[96:99], v[158:161], v[174:177], v[96:99]
	v_mfma_f32_16x16x32_bf16 v[84:87], v[150:153], v[182:185], v[84:87]
	v_mfma_f32_16x16x32_bf16 v[80:83], v[158:161], v[182:185], v[80:83]
	v_mfma_f32_16x16x32_bf16 v[68:71], v[150:153], v[202:205], v[68:71]
	v_mfma_f32_16x16x32_bf16 v[64:67], v[158:161], v[202:205], v[64:67]
	v_mfma_f32_16x16x32_bf16 v[116:119], v[154:157], v[170:173], v[116:119]
	v_mfma_f32_16x16x32_bf16 v[112:115], v[162:165], v[170:173], v[112:115]
	v_mfma_f32_16x16x32_bf16 v[100:103], v[154:157], v[178:181], v[100:103]
	v_mfma_f32_16x16x32_bf16 v[96:99], v[162:165], v[178:181], v[96:99]
	v_mfma_f32_16x16x32_bf16 v[84:87], v[154:157], v[186:189], v[84:87]
	v_mfma_f32_16x16x32_bf16 v[80:83], v[162:165], v[186:189], v[80:83]
	v_mfma_f32_16x16x32_bf16 v[68:71], v[154:157], v[206:209], v[68:71]
	v_mfma_f32_16x16x32_bf16 v[64:67], v[162:165], v[206:209], v[64:67]
	s_setprio 0
	s_barrier
	s_add_i32 s22, s22, s33
	s_mov_b32 m0, s22
	ds_read_b128 v[166:169], v131 offset:49152
	ds_read_b128 v[170:173], v131 offset:50176
	ds_read_b128 v[174:177], v131 offset:51200
	ds_read_b128 v[178:181], v131 offset:52224
	ds_read_b128 v[182:185], v131 offset:53248
	ds_read_b128 v[186:189], v131 offset:54272
	ds_read_b128 v[202:205], v131 offset:55296
	ds_read_b128 v[206:209], v131 offset:56320
	global_load_lds_dwordx4 v192, s[66:67]
	s_add_i32 m0, s22, 0x2000
	s_add_i32 s22, s23, s33
	global_load_lds_dwordx4 v132, s[66:67]
	s_mov_b32 m0, s22
	s_nop 0
	global_load_lds_dwordx4 v192, s[46:47]
	s_add_i32 m0, s22, 0x2000
	s_nop 0
	global_load_lds_dwordx4 v132, s[46:47]
	s_mov_b32 m0, s54
	s_nop 0
	global_load_lds_dwordx4 v128, s[26:27]
	s_mov_b32 m0, s55
	s_nop 0
	global_load_lds_dwordx4 v130, s[26:27]
	s_waitcnt vmcnt(8)
	s_waitcnt lgkmcnt(0)
	s_barrier
	s_setprio 1
	s_waitcnt lgkmcnt(0)
	v_mfma_f32_16x16x32_bf16 v[60:63], v[134:137], v[166:169], v[60:63]
	v_mfma_f32_16x16x32_bf16 v[56:59], v[142:145], v[166:169], v[56:59]
	v_mfma_f32_16x16x32_bf16 v[44:47], v[134:137], v[174:177], v[44:47]
	v_mfma_f32_16x16x32_bf16 v[40:43], v[142:145], v[174:177], v[40:43]
	v_mfma_f32_16x16x32_bf16 v[28:31], v[134:137], v[182:185], v[28:31]
	v_mfma_f32_16x16x32_bf16 v[24:27], v[142:145], v[182:185], v[24:27]
	v_mfma_f32_16x16x32_bf16 v[12:15], v[134:137], v[202:205], v[12:15]
	v_mfma_f32_16x16x32_bf16 v[8:11], v[142:145], v[202:205], v[8:11]
	v_mfma_f32_16x16x32_bf16 v[60:63], v[138:141], v[170:173], v[60:63]
	v_mfma_f32_16x16x32_bf16 v[56:59], v[146:149], v[170:173], v[56:59]
	v_mfma_f32_16x16x32_bf16 v[44:47], v[138:141], v[178:181], v[44:47]
	v_mfma_f32_16x16x32_bf16 v[40:43], v[146:149], v[178:181], v[40:43]
	v_mfma_f32_16x16x32_bf16 v[28:31], v[138:141], v[186:189], v[28:31]
	v_mfma_f32_16x16x32_bf16 v[24:27], v[146:149], v[186:189], v[24:27]
	v_mfma_f32_16x16x32_bf16 v[12:15], v[138:141], v[206:209], v[12:15]
	v_mfma_f32_16x16x32_bf16 v[8:11], v[146:149], v[206:209], v[8:11]
	s_setprio 0
	s_setprio 1
	v_mfma_f32_16x16x32_bf16 v[52:55], v[150:153], v[166:169], v[52:55]
	v_mfma_f32_16x16x32_bf16 v[48:51], v[158:161], v[166:169], v[48:51]
	v_mfma_f32_16x16x32_bf16 v[36:39], v[150:153], v[174:177], v[36:39]
	v_mfma_f32_16x16x32_bf16 v[32:35], v[158:161], v[174:177], v[32:35]
	v_mfma_f32_16x16x32_bf16 v[20:23], v[150:153], v[182:185], v[20:23]
	v_mfma_f32_16x16x32_bf16 v[16:19], v[158:161], v[182:185], v[16:19]
	v_mfma_f32_16x16x32_bf16 v[4:7], v[150:153], v[202:205], v[4:7]
	v_mfma_f32_16x16x32_bf16 v[0:3], v[158:161], v[202:205], v[0:3]
	v_mfma_f32_16x16x32_bf16 v[52:55], v[154:157], v[170:173], v[52:55]
	v_mfma_f32_16x16x32_bf16 v[48:51], v[162:165], v[170:173], v[48:51]
	v_mfma_f32_16x16x32_bf16 v[36:39], v[154:157], v[178:181], v[36:39]
	v_mfma_f32_16x16x32_bf16 v[32:35], v[162:165], v[178:181], v[32:35]
	v_mfma_f32_16x16x32_bf16 v[20:23], v[154:157], v[186:189], v[20:23]
	v_mfma_f32_16x16x32_bf16 v[16:19], v[162:165], v[186:189], v[16:19]
	v_mfma_f32_16x16x32_bf16 v[4:7], v[154:157], v[206:209], v[4:7]
	v_mfma_f32_16x16x32_bf16 v[0:3], v[162:165], v[206:209], v[0:3]
	s_setprio 0
	s_barrier
	s_add_i32 s89, s89, 2
	s_add_u32 s87, s87, 0x100
	s_addc_u32 s88, s88, 0
	s_cmp_gt_u32 s89, 29
	s_mov_b64 s[46:47], s[80:81]
	s_branch .LBB0_716

.LBB0_716:
	s_add_u32 s80, s46, 0x100
	s_addc_u32 s81, s47, 0
	s_cmp_eq_u32 s89, 28
	s_cselect_b32 s28, vcc_lo, s80
	s_cselect_b32 s29, s37, s81
	s_cselect_b32 s23, s21, s88
	s_cselect_b32 s22, s86, s87
	s_add_u32 s26, s28, 0x80
	s_addc_u32 s27, s29, 0
	s_add_u32 s66, s22, 0x80
	s_addc_u32 s67, s23, 0
	s_add_u32 s90, s46, 0x80080
	s_addc_u32 s91, s47, 0
	s_add_u32 s52, s28, 0x80000
	s_addc_u32 s53, s29, 0
	s_add_u32 s56, s22, 0x80000
	s_addc_u32 s57, s23, 0
	s_add_u32 s46, s22, 0x80080
	s_addc_u32 s47, s23, 0
	s_add_i32 s92, 0, 0x10000
	v_add_u32_e32 v133, s92, v129
	s_add_i32 s93, 0, 0x14000
	ds_read_b128 v[134:137], v133
	ds_read_b128 v[138:141], v133 offset:1024
	ds_read_b128 v[142:145], v133 offset:2048
	ds_read_b128 v[146:149], v133 offset:3072
	v_add_u32_e32 v133, s93, v129
	ds_read_b128 v[150:153], v133
	ds_read_b128 v[154:157], v133 offset:1024
	ds_read_b128 v[158:161], v133 offset:2048
	ds_read_b128 v[162:165], v133 offset:3072
	s_add_i32 m0, s0, 0xc000
	ds_read_b128 v[166:169], v131
	ds_read_b128 v[170:173], v131 offset:1024
	ds_read_b128 v[174:177], v131 offset:2048
	ds_read_b128 v[178:181], v131 offset:3072
	ds_read_b128 v[182:185], v131 offset:4096
	ds_read_b128 v[186:189], v131 offset:5120
	ds_read_b128 v[202:205], v131 offset:6144
	ds_read_b128 v[206:209], v131 offset:7168
	global_load_lds_dwordx4 v128, s[90:91]
	s_add_i32 m0, s0, 0xe000
	s_nop 0
	global_load_lds_dwordx4 v130, s[90:91]
	s_waitcnt vmcnt(8)
	s_waitcnt lgkmcnt(0)
	s_barrier
	s_setprio 1
	s_waitcnt lgkmcnt(0)
	v_mfma_f32_16x16x32_bf16 v[124:127], v[134:137], v[166:169], v[124:127]
	v_mfma_f32_16x16x32_bf16 v[120:123], v[142:145], v[166:169], v[120:123]
	v_mfma_f32_16x16x32_bf16 v[108:111], v[134:137], v[174:177], v[108:111]
	v_mfma_f32_16x16x32_bf16 v[104:107], v[142:145], v[174:177], v[104:107]
	v_mfma_f32_16x16x32_bf16 v[92:95], v[134:137], v[182:185], v[92:95]
	v_mfma_f32_16x16x32_bf16 v[88:91], v[142:145], v[182:185], v[88:91]
	v_mfma_f32_16x16x32_bf16 v[76:79], v[134:137], v[202:205], v[76:79]
	v_mfma_f32_16x16x32_bf16 v[72:75], v[142:145], v[202:205], v[72:75]
	v_mfma_f32_16x16x32_bf16 v[124:127], v[138:141], v[170:173], v[124:127]
	v_mfma_f32_16x16x32_bf16 v[120:123], v[146:149], v[170:173], v[120:123]
	v_mfma_f32_16x16x32_bf16 v[108:111], v[138:141], v[178:181], v[108:111]
	v_mfma_f32_16x16x32_bf16 v[104:107], v[146:149], v[178:181], v[104:107]
	v_mfma_f32_16x16x32_bf16 v[92:95], v[138:141], v[186:189], v[92:95]
	v_mfma_f32_16x16x32_bf16 v[88:91], v[146:149], v[186:189], v[88:91]
	v_mfma_f32_16x16x32_bf16 v[76:79], v[138:141], v[206:209], v[76:79]
	v_mfma_f32_16x16x32_bf16 v[72:75], v[146:149], v[206:209], v[72:75]
	s_setprio 0
	s_setprio 1
	v_mfma_f32_16x16x32_bf16 v[116:119], v[150:153], v[166:169], v[116:119]
	v_mfma_f32_16x16x32_bf16 v[112:115], v[158:161], v[166:169], v[112:115]
	v_mfma_f32_16x16x32_bf16 v[100:103], v[150:153], v[174:177], v[100:103]
	v_mfma_f32_16x16x32_bf16 v[96:99], v[158:161], v[174:177], v[96:99]
	v_mfma_f32_16x16x32_bf16 v[84:87], v[150:153], v[182:185], v[84:87]
	v_mfma_f32_16x16x32_bf16 v[80:83], v[158:161], v[182:185], v[80:83]
	v_mfma_f32_16x16x32_bf16 v[68:71], v[150:153], v[202:205], v[68:71]
	v_mfma_f32_16x16x32_bf16 v[64:67], v[158:161], v[202:205], v[64:67]
	v_mfma_f32_16x16x32_bf16 v[116:119], v[154:157], v[170:173], v[116:119]
	v_mfma_f32_16x16x32_bf16 v[112:115], v[162:165], v[170:173], v[112:115]
	v_mfma_f32_16x16x32_bf16 v[100:103], v[154:157], v[178:181], v[100:103]
	v_mfma_f32_16x16x32_bf16 v[96:99], v[162:165], v[178:181], v[96:99]
	v_mfma_f32_16x16x32_bf16 v[84:87], v[154:157], v[186:189], v[84:87]
	v_mfma_f32_16x16x32_bf16 v[80:83], v[162:165], v[186:189], v[80:83]
	v_mfma_f32_16x16x32_bf16 v[68:71], v[154:157], v[206:209], v[68:71]
	v_mfma_f32_16x16x32_bf16 v[64:67], v[162:165], v[206:209], v[64:67]
	s_setprio 0
	s_barrier
	s_add_i32 s90, s92, s33
	s_mov_b32 m0, s90
	ds_read_b128 v[166:169], v131 offset:16384
	ds_read_b128 v[170:173], v131 offset:17408
	ds_read_b128 v[174:177], v131 offset:18432
	ds_read_b128 v[178:181], v131 offset:19456
	ds_read_b128 v[182:185], v131 offset:20480
	ds_read_b128 v[186:189], v131 offset:21504
	ds_read_b128 v[202:205], v131 offset:22528
	ds_read_b128 v[206:209], v131 offset:23552
	global_load_lds_dwordx4 v192, s[22:23]
	s_add_i32 m0, s90, 0x2000
	s_nop 0
	global_load_lds_dwordx4 v132, s[22:23]
	s_add_i32 s22, s93, s33
	s_mov_b32 m0, s22
	s_nop 0
	global_load_lds_dwordx4 v192, s[56:57]
	s_add_i32 m0, s22, 0x2000
	s_nop 0
	global_load_lds_dwordx4 v132, s[56:57]
	s_mov_b32 m0, s0
	s_nop 0
	global_load_lds_dwordx4 v128, s[28:29]
	s_mov_b32 m0, s1
	s_nop 0
	global_load_lds_dwordx4 v130, s[28:29]
	s_waitcnt vmcnt(8)
	s_waitcnt lgkmcnt(0)
	s_barrier
	s_setprio 1
	s_waitcnt lgkmcnt(0)
	v_mfma_f32_16x16x32_bf16 v[60:63], v[134:137], v[166:169], v[60:63]
	v_mfma_f32_16x16x32_bf16 v[56:59], v[142:145], v[166:169], v[56:59]
	v_mfma_f32_16x16x32_bf16 v[44:47], v[134:137], v[174:177], v[44:47]
	v_mfma_f32_16x16x32_bf16 v[40:43], v[142:145], v[174:177], v[40:43]
	v_mfma_f32_16x16x32_bf16 v[28:31], v[134:137], v[182:185], v[28:31]
	v_mfma_f32_16x16x32_bf16 v[24:27], v[142:145], v[182:185], v[24:27]
	v_mfma_f32_16x16x32_bf16 v[12:15], v[134:137], v[202:205], v[12:15]
	v_mfma_f32_16x16x32_bf16 v[8:11], v[142:145], v[202:205], v[8:11]
	v_mfma_f32_16x16x32_bf16 v[60:63], v[138:141], v[170:173], v[60:63]
	v_mfma_f32_16x16x32_bf16 v[56:59], v[146:149], v[170:173], v[56:59]
	v_mfma_f32_16x16x32_bf16 v[44:47], v[138:141], v[178:181], v[44:47]
	v_mfma_f32_16x16x32_bf16 v[40:43], v[146:149], v[178:181], v[40:43]
	v_mfma_f32_16x16x32_bf16 v[28:31], v[138:141], v[186:189], v[28:31]
	v_mfma_f32_16x16x32_bf16 v[24:27], v[146:149], v[186:189], v[24:27]
	v_mfma_f32_16x16x32_bf16 v[12:15], v[138:141], v[206:209], v[12:15]
	v_mfma_f32_16x16x32_bf16 v[8:11], v[146:149], v[206:209], v[8:11]
	s_setprio 0
	s_setprio 1
	v_mfma_f32_16x16x32_bf16 v[52:55], v[150:153], v[166:169], v[52:55]
	v_mfma_f32_16x16x32_bf16 v[48:51], v[158:161], v[166:169], v[48:51]
	v_mfma_f32_16x16x32_bf16 v[36:39], v[150:153], v[174:177], v[36:39]
	v_mfma_f32_16x16x32_bf16 v[32:35], v[158:161], v[174:177], v[32:35]
	v_mfma_f32_16x16x32_bf16 v[20:23], v[150:153], v[182:185], v[20:23]
	v_mfma_f32_16x16x32_bf16 v[16:19], v[158:161], v[182:185], v[16:19]
	v_mfma_f32_16x16x32_bf16 v[4:7], v[150:153], v[202:205], v[4:7]
	v_mfma_f32_16x16x32_bf16 v[0:3], v[158:161], v[202:205], v[0:3]
	v_mfma_f32_16x16x32_bf16 v[52:55], v[154:157], v[170:173], v[52:55]
	v_mfma_f32_16x16x32_bf16 v[48:51], v[162:165], v[170:173], v[48:51]
	v_mfma_f32_16x16x32_bf16 v[36:39], v[154:157], v[178:181], v[36:39]
	v_mfma_f32_16x16x32_bf16 v[32:35], v[162:165], v[178:181], v[32:35]
	v_mfma_f32_16x16x32_bf16 v[20:23], v[154:157], v[186:189], v[20:23]
	v_mfma_f32_16x16x32_bf16 v[16:19], v[162:165], v[186:189], v[16:19]
	v_mfma_f32_16x16x32_bf16 v[4:7], v[154:157], v[206:209], v[4:7]
	v_mfma_f32_16x16x32_bf16 v[0:3], v[162:165], v[206:209], v[0:3]
	s_setprio 0
	s_barrier
	s_add_i32 s22, 0, 0x18000
	v_add_u32_e32 v133, s22, v129
	s_add_i32 s23, 0, 0x1c000
	ds_read_b128 v[134:137], v133
	ds_read_b128 v[138:141], v133 offset:1024
	ds_read_b128 v[142:145], v133 offset:2048
	ds_read_b128 v[146:149], v133 offset:3072
	v_add_u32_e32 v133, s23, v129
	ds_read_b128 v[150:153], v133
	ds_read_b128 v[154:157], v133 offset:1024
	ds_read_b128 v[158:161], v133 offset:2048
	ds_read_b128 v[162:165], v133 offset:3072
	s_mov_b32 m0, s34
	ds_read_b128 v[166:169], v131 offset:32768
	ds_read_b128 v[170:173], v131 offset:33792
	ds_read_b128 v[174:177], v131 offset:34816
	ds_read_b128 v[178:181], v131 offset:35840
	ds_read_b128 v[182:185], v131 offset:36864
	ds_read_b128 v[186:189], v131 offset:37888
	ds_read_b128 v[202:205], v131 offset:38912
	ds_read_b128 v[206:209], v131 offset:39936
	global_load_lds_dwordx4 v128, s[52:53]
	s_mov_b32 m0, s35
	s_nop 0
	global_load_lds_dwordx4 v130, s[52:53]
	s_waitcnt vmcnt(8)
	s_waitcnt lgkmcnt(0)
	s_barrier
	s_setprio 1
	s_waitcnt lgkmcnt(0)
	v_mfma_f32_16x16x32_bf16 v[124:127], v[134:137], v[166:169], v[124:127]
	v_mfma_f32_16x16x32_bf16 v[120:123], v[142:145], v[166:169], v[120:123]
	v_mfma_f32_16x16x32_bf16 v[108:111], v[134:137], v[174:177], v[108:111]
	v_mfma_f32_16x16x32_bf16 v[104:107], v[142:145], v[174:177], v[104:107]
	v_mfma_f32_16x16x32_bf16 v[92:95], v[134:137], v[182:185], v[92:95]
	v_mfma_f32_16x16x32_bf16 v[88:91], v[142:145], v[182:185], v[88:91]
	v_mfma_f32_16x16x32_bf16 v[76:79], v[134:137], v[202:205], v[76:79]
	v_mfma_f32_16x16x32_bf16 v[72:75], v[142:145], v[202:205], v[72:75]
	v_mfma_f32_16x16x32_bf16 v[124:127], v[138:141], v[170:173], v[124:127]
	v_mfma_f32_16x16x32_bf16 v[120:123], v[146:149], v[170:173], v[120:123]
	v_mfma_f32_16x16x32_bf16 v[108:111], v[138:141], v[178:181], v[108:111]
	v_mfma_f32_16x16x32_bf16 v[104:107], v[146:149], v[178:181], v[104:107]
	v_mfma_f32_16x16x32_bf16 v[92:95], v[138:141], v[186:189], v[92:95]
	v_mfma_f32_16x16x32_bf16 v[88:91], v[146:149], v[186:189], v[88:91]
	v_mfma_f32_16x16x32_bf16 v[76:79], v[138:141], v[206:209], v[76:79]
	v_mfma_f32_16x16x32_bf16 v[72:75], v[146:149], v[206:209], v[72:75]
	s_setprio 0
	s_setprio 1
	v_mfma_f32_16x16x32_bf16 v[116:119], v[150:153], v[166:169], v[116:119]
	v_mfma_f32_16x16x32_bf16 v[112:115], v[158:161], v[166:169], v[112:115]
	v_mfma_f32_16x16x32_bf16 v[100:103], v[150:153], v[174:177], v[100:103]
	v_mfma_f32_16x16x32_bf16 v[96:99], v[158:161], v[174:177], v[96:99]
	v_mfma_f32_16x16x32_bf16 v[84:87], v[150:153], v[182:185], v[84:87]
	v_mfma_f32_16x16x32_bf16 v[80:83], v[158:161], v[182:185], v[80:83]
	v_mfma_f32_16x16x32_bf16 v[68:71], v[150:153], v[202:205], v[68:71]
	v_mfma_f32_16x16x32_bf16 v[64:67], v[158:161], v[202:205], v[64:67]
	v_mfma_f32_16x16x32_bf16 v[116:119], v[154:157], v[170:173], v[116:119]
	v_mfma_f32_16x16x32_bf16 v[112:115], v[162:165], v[170:173], v[112:115]
	v_mfma_f32_16x16x32_bf16 v[100:103], v[154:157], v[178:181], v[100:103]
	v_mfma_f32_16x16x32_bf16 v[96:99], v[162:165], v[178:181], v[96:99]
	v_mfma_f32_16x16x32_bf16 v[84:87], v[154:157], v[186:189], v[84:87]
	v_mfma_f32_16x16x32_bf16 v[80:83], v[162:165], v[186:189], v[80:83]
	v_mfma_f32_16x16x32_bf16 v[68:71], v[154:157], v[206:209], v[68:71]
	v_mfma_f32_16x16x32_bf16 v[64:67], v[162:165], v[206:209], v[64:67]
	s_setprio 0
	s_barrier
; #define PG8_MMA(ai, bj, At, Bt) do { __builtin_amdgcn_s_setprio(1); _Pragma("unroll") for (int m = 0; m < 4; ++m) _Pragma("unroll") for (int n = 0; n < 2; ++n) _Pragma("unroll") for (int k = 0; k < 2; ++k) \
;         acc[ai][bj][m][n] = __builtin_amdgcn_mfma_f32_16x16x32_bf16(Bt[n][k], At[m][k], acc[ai][bj][m][n], 0, 0, 0); __builtin_amdgcn_s_setprio(0); } while (0)
;     __device__ __forceinline__ void operator()(const f32x4 (&acc)[2][2][4][2], const Unit& u, int wr, int wc, int fr, int fq) const {
;     ...
;             for (int m = 0; m < 4; ++m) { const int r = row0 + ai * HALF + m * 16;
;                 bf16_t* rowp = hm ? base + ((size_t)((r >> 12) * 8 + (colt >> 7)) * 4096 + (r & 4095)) * 128 + wc * 32 + 8 * fq : base + (size_t)r * ldc + col0;
;     ...
;         { const int tmid = (TSW > 0 && TSW < nt) ? TSW : nt;
;           _Pragma("unroll 1") for (int t = 0; t < tmid; t += 2) { PG8_BODY(PG8_MMA) }
	s_add_i32 s22, s22, s33
	s_mov_b32 m0, s22
	ds_read_b128 v[166:169], v131 offset:49152
	ds_read_b128 v[170:173], v131 offset:50176
	ds_read_b128 v[174:177], v131 offset:51200
	ds_read_b128 v[178:181], v131 offset:52224
	ds_read_b128 v[182:185], v131 offset:53248
	ds_read_b128 v[186:189], v131 offset:54272
	ds_read_b128 v[202:205], v131 offset:55296
	ds_read_b128 v[206:209], v131 offset:56320
	global_load_lds_dwordx4 v192, s[66:67]
	s_add_i32 m0, s22, 0x2000
	s_add_i32 s22, s23, s33
	global_load_lds_dwordx4 v132, s[66:67]
	s_mov_b32 m0, s22
	s_nop 0
	global_load_lds_dwordx4 v192, s[46:47]
	s_add_i32 m0, s22, 0x2000
	s_nop 0
	global_load_lds_dwordx4 v132, s[46:47]
	s_mov_b32 m0, s54
	s_nop 0
	global_load_lds_dwordx4 v128, s[26:27]
	s_mov_b32 m0, s55
	s_nop 0
	global_load_lds_dwordx4 v130, s[26:27]
	s_waitcnt vmcnt(8)
	s_waitcnt lgkmcnt(0)
	s_barrier
	s_setprio 1
	s_waitcnt lgkmcnt(0)
	v_mfma_f32_16x16x32_bf16 v[60:63], v[134:137], v[166:169], v[60:63]
	v_mfma_f32_16x16x32_bf16 v[56:59], v[142:145], v[166:169], v[56:59]
	v_mfma_f32_16x16x32_bf16 v[44:47], v[134:137], v[174:177], v[44:47]
	v_mfma_f32_16x16x32_bf16 v[40:43], v[142:145], v[174:177], v[40:43]
	v_mfma_f32_16x16x32_bf16 v[28:31], v[134:137], v[182:185], v[28:31]
	v_mfma_f32_16x16x32_bf16 v[24:27], v[142:145], v[182:185], v[24:27]
	v_mfma_f32_16x16x32_bf16 v[12:15], v[134:137], v[202:205], v[12:15]
	v_mfma_f32_16x16x32_bf16 v[8:11], v[142:145], v[202:205], v[8:11]
	v_mfma_f32_16x16x32_bf16 v[60:63], v[138:141], v[170:173], v[60:63]
	v_mfma_f32_16x16x32_bf16 v[56:59], v[146:149], v[170:173], v[56:59]
	v_mfma_f32_16x16x32_bf16 v[44:47], v[138:141], v[178:181], v[44:47]
	v_mfma_f32_16x16x32_bf16 v[40:43], v[146:149], v[178:181], v[40:43]
	v_mfma_f32_16x16x32_bf16 v[28:31], v[138:141], v[186:189], v[28:31]
	v_mfma_f32_16x16x32_bf16 v[24:27], v[146:149], v[186:189], v[24:27]
	v_mfma_f32_16x16x32_bf16 v[12:15], v[138:141], v[206:209], v[12:15]
	v_mfma_f32_16x16x32_bf16 v[8:11], v[146:149], v[206:209], v[8:11]
	s_setprio 0
	s_setprio 1
	v_mfma_f32_16x16x32_bf16 v[52:55], v[150:153], v[166:169], v[52:55]
	v_mfma_f32_16x16x32_bf16 v[48:51], v[158:161], v[166:169], v[48:51]
	v_mfma_f32_16x16x32_bf16 v[36:39], v[150:153], v[174:177], v[36:39]
	v_mfma_f32_16x16x32_bf16 v[32:35], v[158:161], v[174:177], v[32:35]
	v_mfma_f32_16x16x32_bf16 v[20:23], v[150:153], v[182:185], v[20:23]
	v_mfma_f32_16x16x32_bf16 v[16:19], v[158:161], v[182:185], v[16:19]
	v_mfma_f32_16x16x32_bf16 v[4:7], v[150:153], v[202:205], v[4:7]
	v_mfma_f32_16x16x32_bf16 v[0:3], v[158:161], v[202:205], v[0:3]
	v_mfma_f32_16x16x32_bf16 v[52:55], v[154:157], v[170:173], v[52:55]
	v_mfma_f32_16x16x32_bf16 v[48:51], v[162:165], v[170:173], v[48:51]
	v_mfma_f32_16x16x32_bf16 v[36:39], v[154:157], v[178:181], v[36:39]
	v_mfma_f32_16x16x32_bf16 v[32:35], v[162:165], v[178:181], v[32:35]
	v_mfma_f32_16x16x32_bf16 v[20:23], v[154:157], v[186:189], v[20:23]
	v_mfma_f32_16x16x32_bf16 v[16:19], v[162:165], v[186:189], v[16:19]
	v_mfma_f32_16x16x32_bf16 v[4:7], v[154:157], v[206:209], v[4:7]
	v_mfma_f32_16x16x32_bf16 v[0:3], v[162:165], v[206:209], v[0:3]
	s_setprio 0
	s_barrier
	s_add_i32 s89, s89, 2
	s_add_u32 s87, s87, 0x100
	s_addc_u32 s88, s88, 0
	s_mov_b64 s[46:47], s[80:81]
	s_cmp_eq_u32 s89, 28
	s_cbranch_scc1 mk_p5_chk
	s_cmp_gt_u32 s89, 29
	s_cbranch_scc0 .LBB0_716
	s_branch mk_p5_exit
mk_p5_chk:
	s_cmp_lg_u64 s[40:41], 0
	s_cbranch_scc0 .LBB0_716
	s_lshl_b32 s98, s74, 8
	s_add_i32 s98, s98, s48
	s_lshl_b32 s98, s98, 14
	s_lshl_b32 s99, s75, 8
	s_or_b32 s99, s99, s50
	s_lshl_b32 s99, s99, 1
	s_add_u32 s98, s98, s99
	s_add_u32 s98, s76, s98
	s_addc_u32 s99, s77, 0
	s_add_u32 s100, s98, 0x200000
	s_addc_u32 s101, s99, 0
	s_add_u32 s80, s46, 0x100
	s_addc_u32 s81, s47, 0
	s_cmp_eq_u32 s89, 28
	s_cselect_b32 s28, vcc_lo, s80
	s_cselect_b32 s29, s37, s81
	s_cselect_b32 s23, s21, s88
	s_cselect_b32 s22, s86, s87
	s_add_u32 s26, s28, 0x80
	s_addc_u32 s27, s29, 0
	s_add_u32 s66, s22, 0x80
	s_addc_u32 s67, s23, 0
	s_add_u32 s90, s46, 0x80080
	s_addc_u32 s91, s47, 0
	s_add_u32 s52, s28, 0x80000
	s_addc_u32 s53, s29, 0
	s_add_u32 s56, s22, 0x80000
	s_addc_u32 s57, s23, 0
	s_add_u32 s46, s22, 0x80080
	s_addc_u32 s47, s23, 0
	s_add_i32 s92, 0, 0x10000
	v_add_u32_e32 v133, s92, v129
	s_add_i32 s93, 0, 0x14000
	ds_read_b128 v[134:137], v133
	ds_read_b128 v[138:141], v133 offset:1024
	ds_read_b128 v[142:145], v133 offset:2048
	ds_read_b128 v[146:149], v133 offset:3072
	v_add_u32_e32 v133, s93, v129
	ds_read_b128 v[150:153], v133
	ds_read_b128 v[154:157], v133 offset:1024
	ds_read_b128 v[158:161], v133 offset:2048
	ds_read_b128 v[162:165], v133 offset:3072
	s_add_i32 m0, s0, 0xc000
	ds_read_b128 v[166:169], v131
	ds_read_b128 v[170:173], v131 offset:1024
	ds_read_b128 v[174:177], v131 offset:2048
	ds_read_b128 v[178:181], v131 offset:3072
	ds_read_b128 v[182:185], v131 offset:4096
	ds_read_b128 v[186:189], v131 offset:5120
	ds_read_b128 v[202:205], v131 offset:6144
	ds_read_b128 v[206:209], v131 offset:7168
	global_load_lds_dwordx4 v128, s[90:91]
	s_add_i32 m0, s0, 0xe000
	s_nop 0
	global_load_lds_dwordx4 v130, s[90:91]
	s_waitcnt vmcnt(8)
	s_waitcnt lgkmcnt(0)
	s_barrier
	s_setprio 1
	s_waitcnt lgkmcnt(0)
	v_mfma_f32_16x16x32_bf16 v[124:127], v[134:137], v[166:169], v[124:127]
	v_mfma_f32_16x16x32_bf16 v[120:123], v[142:145], v[166:169], v[120:123]
	v_mfma_f32_16x16x32_bf16 v[108:111], v[134:137], v[174:177], v[108:111]
	v_mfma_f32_16x16x32_bf16 v[104:107], v[142:145], v[174:177], v[104:107]
	v_mfma_f32_16x16x32_bf16 v[92:95], v[134:137], v[182:185], v[92:95]
	v_mfma_f32_16x16x32_bf16 v[88:91], v[142:145], v[182:185], v[88:91]
	v_mfma_f32_16x16x32_bf16 v[76:79], v[134:137], v[202:205], v[76:79]
	v_mfma_f32_16x16x32_bf16 v[72:75], v[142:145], v[202:205], v[72:75]
	v_mfma_f32_16x16x32_bf16 v[124:127], v[138:141], v[170:173], v[124:127]
	v_mfma_f32_16x16x32_bf16 v[120:123], v[146:149], v[170:173], v[120:123]
	v_mfma_f32_16x16x32_bf16 v[108:111], v[138:141], v[178:181], v[108:111]
	v_mfma_f32_16x16x32_bf16 v[104:107], v[146:149], v[178:181], v[104:107]
	v_mfma_f32_16x16x32_bf16 v[92:95], v[138:141], v[186:189], v[92:95]
	v_mfma_f32_16x16x32_bf16 v[88:91], v[146:149], v[186:189], v[88:91]
	v_mfma_f32_16x16x32_bf16 v[76:79], v[138:141], v[206:209], v[76:79]
	v_mfma_f32_16x16x32_bf16 v[72:75], v[146:149], v[206:209], v[72:75]
	s_setprio 0
	s_setprio 1
	v_mfma_f32_16x16x32_bf16 v[116:119], v[150:153], v[166:169], v[116:119]
	v_mfma_f32_16x16x32_bf16 v[112:115], v[158:161], v[166:169], v[112:115]
	v_mfma_f32_16x16x32_bf16 v[100:103], v[150:153], v[174:177], v[100:103]
	v_mfma_f32_16x16x32_bf16 v[96:99], v[158:161], v[174:177], v[96:99]
	v_mfma_f32_16x16x32_bf16 v[84:87], v[150:153], v[182:185], v[84:87]
	v_mfma_f32_16x16x32_bf16 v[80:83], v[158:161], v[182:185], v[80:83]
	v_mfma_f32_16x16x32_bf16 v[68:71], v[150:153], v[202:205], v[68:71]
	v_mfma_f32_16x16x32_bf16 v[64:67], v[158:161], v[202:205], v[64:67]
	v_mfma_f32_16x16x32_bf16 v[116:119], v[154:157], v[170:173], v[116:119]
	v_mfma_f32_16x16x32_bf16 v[112:115], v[162:165], v[170:173], v[112:115]
	v_mfma_f32_16x16x32_bf16 v[100:103], v[154:157], v[178:181], v[100:103]
	v_mfma_f32_16x16x32_bf16 v[96:99], v[162:165], v[178:181], v[96:99]
	v_mfma_f32_16x16x32_bf16 v[84:87], v[154:157], v[186:189], v[84:87]
	v_mfma_f32_16x16x32_bf16 v[80:83], v[162:165], v[186:189], v[80:83]
	v_mfma_f32_16x16x32_bf16 v[68:71], v[154:157], v[206:209], v[68:71]
	v_mfma_f32_16x16x32_bf16 v[64:67], v[162:165], v[206:209], v[64:67]
	s_setprio 0
	s_barrier
	s_add_i32 s90, s92, s33
	s_mov_b32 m0, s90
	ds_read_b128 v[166:169], v131 offset:16384
	ds_read_b128 v[170:173], v131 offset:17408
	ds_read_b128 v[174:177], v131 offset:18432
	ds_read_b128 v[178:181], v131 offset:19456
	ds_read_b128 v[182:185], v131 offset:20480
	ds_read_b128 v[186:189], v131 offset:21504
	ds_read_b128 v[202:205], v131 offset:22528
	ds_read_b128 v[206:209], v131 offset:23552
	global_load_lds_dwordx4 v192, s[22:23]
	s_add_i32 m0, s90, 0x2000
	s_nop 0
	global_load_lds_dwordx4 v132, s[22:23]
	s_add_i32 s22, s93, s33
	s_mov_b32 m0, s22
	s_nop 0
	global_load_lds_dwordx4 v192, s[56:57]
	s_add_i32 m0, s22, 0x2000
	s_nop 0
	global_load_lds_dwordx4 v132, s[56:57]
	s_mov_b32 m0, s0
	s_nop 0
	global_load_lds_dwordx4 v128, s[28:29]
	s_mov_b32 m0, s1
	s_nop 0
	global_load_lds_dwordx4 v130, s[28:29]
	s_waitcnt vmcnt(8)
	s_waitcnt lgkmcnt(0)
	s_barrier
	s_setprio 1
	s_waitcnt lgkmcnt(0)
	v_mfma_f32_16x16x32_bf16 v[60:63], v[134:137], v[166:169], v[60:63]
	v_mfma_f32_16x16x32_bf16 v[56:59], v[142:145], v[166:169], v[56:59]
	v_mfma_f32_16x16x32_bf16 v[44:47], v[134:137], v[174:177], v[44:47]
	v_mfma_f32_16x16x32_bf16 v[40:43], v[142:145], v[174:177], v[40:43]
	v_mfma_f32_16x16x32_bf16 v[28:31], v[134:137], v[182:185], v[28:31]
	v_mfma_f32_16x16x32_bf16 v[24:27], v[142:145], v[182:185], v[24:27]
	v_mfma_f32_16x16x32_bf16 v[12:15], v[134:137], v[202:205], v[12:15]
	v_mfma_f32_16x16x32_bf16 v[8:11], v[142:145], v[202:205], v[8:11]
	v_mfma_f32_16x16x32_bf16 v[60:63], v[138:141], v[170:173], v[60:63]
	v_mfma_f32_16x16x32_bf16 v[56:59], v[146:149], v[170:173], v[56:59]
	v_mfma_f32_16x16x32_bf16 v[44:47], v[138:141], v[178:181], v[44:47]
	v_mfma_f32_16x16x32_bf16 v[40:43], v[146:149], v[178:181], v[40:43]
	v_mfma_f32_16x16x32_bf16 v[28:31], v[138:141], v[186:189], v[28:31]
	v_mfma_f32_16x16x32_bf16 v[24:27], v[146:149], v[186:189], v[24:27]
	v_mfma_f32_16x16x32_bf16 v[12:15], v[138:141], v[206:209], v[12:15]
	v_mfma_f32_16x16x32_bf16 v[8:11], v[146:149], v[206:209], v[8:11]
	s_setprio 0
	s_setprio 1
	v_mfma_f32_16x16x32_bf16 v[52:55], v[150:153], v[166:169], v[52:55]
	v_mfma_f32_16x16x32_bf16 v[48:51], v[158:161], v[166:169], v[48:51]
	v_mfma_f32_16x16x32_bf16 v[36:39], v[150:153], v[174:177], v[36:39]
	v_mfma_f32_16x16x32_bf16 v[32:35], v[158:161], v[174:177], v[32:35]
	v_mfma_f32_16x16x32_bf16 v[20:23], v[150:153], v[182:185], v[20:23]
	v_mfma_f32_16x16x32_bf16 v[16:19], v[158:161], v[182:185], v[16:19]
	v_mfma_f32_16x16x32_bf16 v[4:7], v[150:153], v[202:205], v[4:7]
	v_mfma_f32_16x16x32_bf16 v[0:3], v[158:161], v[202:205], v[0:3]
	v_mfma_f32_16x16x32_bf16 v[52:55], v[154:157], v[170:173], v[52:55]
	v_mfma_f32_16x16x32_bf16 v[48:51], v[162:165], v[170:173], v[48:51]
	v_mfma_f32_16x16x32_bf16 v[36:39], v[154:157], v[178:181], v[36:39]
	v_mfma_f32_16x16x32_bf16 v[32:35], v[162:165], v[178:181], v[32:35]
	v_mfma_f32_16x16x32_bf16 v[20:23], v[154:157], v[186:189], v[20:23]
	v_mfma_f32_16x16x32_bf16 v[16:19], v[162:165], v[186:189], v[16:19]
	v_mfma_f32_16x16x32_bf16 v[4:7], v[154:157], v[206:209], v[4:7]
	v_mfma_f32_16x16x32_bf16 v[0:3], v[162:165], v[206:209], v[0:3]
	s_setprio 0
	s_barrier
;     __device__ __forceinline__ const char* a(const Unit& u) const { return (const char*)A + (size_t)u.pm * 2 * hA(); }
;     __device__ __forceinline__ const char* b(const Unit& u) const { return (const char*)Bt + (size_t)u.pn * 2 * hB() + (size_t)(u.pm >> gshift) * goff; }
;     __device__ __forceinline__ const char* a(const Unit& u) const { return (const char*)A + (size_t)u.pm * 2 * hA(); }
;     __device__ __forceinline__ const char* b(const Unit& u) const { return (const char*)Bt + (size_t)((u.pn >> 4) * 4096 + (u.pn & 15) * 16) * 1024 * 2 + (size_t)(u.pm >> 1) * 512; }
;     __device__ __forceinline__ const char* a(const Unit&) const { return (const char*)A; }
;     __device__ __forceinline__ const char* b(const Unit& u) const { return (const char*)Bt + ((size_t)(((u.pm >> 4) * 1024 + u.pn * 256) * 16 + (u.pm & 15)) * 512) * 2; }
;     __device__ __forceinline__ void operator()(const f32x4 (&acc)[2][2][4][2], const Unit& u, int wr, int wc, int fr, int fq) const {
;     ...
;             for (int m = 0; m < 4; ++m) { const int r = row0 + ai * HALF + m * 16;
;                 bf16_t* rowp = hm ? base + ((size_t)((r >> 12) * 8 + (colt >> 7)) * 4096 + (r & 4095)) * 128 + wc * 32 + 8 * fq : base + (size_t)r * ldc + col0;
;                 float rv = sc; if (RS == 1) rv *= rsv[ai][m]; if (RS == 2) rv *= __builtin_amdgcn_rsqf(rsv[ai][m] * (1.0f / DM) + EPS);
; #pragma unroll
;                 for (int bj = 0; bj < 2; ++bj) { f32x4 v0 = acc[ai][bj][m][0] * rv, v1 = acc[ai][bj][m][1] * rv;
;                     if (CS) { v0 = v0 * cv[bj][0]; v1 = v1 * cv[bj][1]; }
;                     if (ACT == 2) {
; #pragma unroll
;                         for (int e = 0; e < 4; ++e) { float a = v0[e] > 0.f ? v0[e] : 0.f, b = v1[e] > 0.f ? v1[e] : 0.f; v0[e] = a * a; v1[e] = b * b; } }
;                     if (k8) {
;                         u32x2 w8; w8.x = pk_fp8x4(v0); w8.y = pk_fp8x4(v1);
;                         *(u32x2*)((unsigned char*)base + ((size_t)((r >> 12) * 8 + (colt >> 7) + bj) * 4096 + (r & 4095)) * 128 + wc * 32 + 8 * fq) = w8;
;                     } else {
;                     u32x4 w; w.x = cvt_pk_bf16(v0[0], v0[1]); w.y = cvt_pk_bf16(v0[2], v0[3]); w.z = cvt_pk_bf16(v1[0], v1[1]); w.w = cvt_pk_bf16(v1[2], v1[3]);
;                     *(u32x4*)(rowp + bj * bstep) = w; } } }
	s_add_i32 s22, 0, 0x18000
	v_add_u32_e32 v133, s22, v129
	s_add_i32 s23, 0, 0x1c000
	ds_read_b128 v[134:137], v133
	ds_read_b128 v[138:141], v133 offset:1024
	ds_read_b128 v[142:145], v133 offset:2048
	ds_read_b128 v[146:149], v133 offset:3072
	v_add_u32_e32 v133, s23, v129
	ds_read_b128 v[150:153], v133
	ds_read_b128 v[154:157], v133 offset:1024
	ds_read_b128 v[158:161], v133 offset:2048
	ds_read_b128 v[162:165], v133 offset:3072
	s_mov_b32 m0, s34
	ds_read_b128 v[166:169], v131 offset:32768
	ds_read_b128 v[170:173], v131 offset:33792
	ds_read_b128 v[174:177], v131 offset:34816
	ds_read_b128 v[178:181], v131 offset:35840
	ds_read_b128 v[182:185], v131 offset:36864
	ds_read_b128 v[186:189], v131 offset:37888
	ds_read_b128 v[202:205], v131 offset:38912
	ds_read_b128 v[206:209], v131 offset:39936
	global_load_lds_dwordx4 v128, s[52:53]
	s_mov_b32 m0, s35
	s_nop 0
	global_load_lds_dwordx4 v130, s[52:53]
	s_waitcnt vmcnt(8)
	s_waitcnt lgkmcnt(0)
	s_barrier
	s_setprio 1
	s_waitcnt lgkmcnt(0)
	v_mfma_f32_16x16x32_bf16 v[124:127], v[134:137], v[166:169], v[124:127]
	v_mfma_f32_16x16x32_bf16 v[120:123], v[142:145], v[166:169], v[120:123]
	v_mfma_f32_16x16x32_bf16 v[108:111], v[134:137], v[174:177], v[108:111]
	v_mfma_f32_16x16x32_bf16 v[104:107], v[142:145], v[174:177], v[104:107]
	v_mfma_f32_16x16x32_bf16 v[92:95], v[134:137], v[182:185], v[92:95]
	v_mfma_f32_16x16x32_bf16 v[88:91], v[142:145], v[182:185], v[88:91]
	v_mfma_f32_16x16x32_bf16 v[76:79], v[134:137], v[202:205], v[76:79]
	v_mfma_f32_16x16x32_bf16 v[72:75], v[142:145], v[202:205], v[72:75]
	v_mfma_f32_16x16x32_bf16 v[124:127], v[138:141], v[170:173], v[124:127]
	v_mfma_f32_16x16x32_bf16 v[120:123], v[146:149], v[170:173], v[120:123]
	v_mfma_f32_16x16x32_bf16 v[108:111], v[138:141], v[178:181], v[108:111]
	v_mfma_f32_16x16x32_bf16 v[104:107], v[146:149], v[178:181], v[104:107]
	v_mfma_f32_16x16x32_bf16 v[92:95], v[138:141], v[186:189], v[92:95]
	v_mfma_f32_16x16x32_bf16 v[88:91], v[146:149], v[186:189], v[88:91]
	v_mfma_f32_16x16x32_bf16 v[76:79], v[138:141], v[206:209], v[76:79]
	v_mfma_f32_16x16x32_bf16 v[72:75], v[146:149], v[206:209], v[72:75]
	s_setprio 0
	s_setprio 1
	v_mfma_f32_16x16x32_bf16 v[116:119], v[150:153], v[166:169], v[116:119]
	v_mfma_f32_16x16x32_bf16 v[112:115], v[158:161], v[166:169], v[112:115]
	v_mfma_f32_16x16x32_bf16 v[100:103], v[150:153], v[174:177], v[100:103]
	v_mfma_f32_16x16x32_bf16 v[96:99], v[158:161], v[174:177], v[96:99]
	v_mfma_f32_16x16x32_bf16 v[84:87], v[150:153], v[182:185], v[84:87]
	v_mfma_f32_16x16x32_bf16 v[80:83], v[158:161], v[182:185], v[80:83]
	v_mfma_f32_16x16x32_bf16 v[68:71], v[150:153], v[202:205], v[68:71]
	v_mfma_f32_16x16x32_bf16 v[64:67], v[158:161], v[202:205], v[64:67]
	v_mfma_f32_16x16x32_bf16 v[116:119], v[154:157], v[170:173], v[116:119]
	v_mfma_f32_16x16x32_bf16 v[112:115], v[162:165], v[170:173], v[112:115]
	v_mfma_f32_16x16x32_bf16 v[100:103], v[154:157], v[178:181], v[100:103]
	v_mfma_f32_16x16x32_bf16 v[96:99], v[162:165], v[178:181], v[96:99]
	v_mfma_f32_16x16x32_bf16 v[84:87], v[154:157], v[186:189], v[84:87]
	v_mfma_f32_16x16x32_bf16 v[80:83], v[162:165], v[186:189], v[80:83]
	v_mfma_f32_16x16x32_bf16 v[68:71], v[154:157], v[206:209], v[68:71]
	v_mfma_f32_16x16x32_bf16 v[64:67], v[162:165], v[206:209], v[64:67]
	s_setprio 0
	s_barrier
	s_add_i32 s22, s22, s33
	s_mov_b32 m0, s22
	ds_read_b128 v[166:169], v131 offset:49152
	ds_read_b128 v[170:173], v131 offset:50176
	ds_read_b128 v[174:177], v131 offset:51200
	ds_read_b128 v[178:181], v131 offset:52224
	ds_read_b128 v[182:185], v131 offset:53248
	ds_read_b128 v[186:189], v131 offset:54272
	ds_read_b128 v[202:205], v131 offset:55296
	ds_read_b128 v[206:209], v131 offset:56320
	global_load_lds_dwordx4 v192, s[66:67]
	s_add_i32 m0, s22, 0x2000
	s_add_i32 s22, s23, s33
	global_load_lds_dwordx4 v132, s[66:67]
	s_mov_b32 m0, s22
	s_nop 0
	global_load_lds_dwordx4 v192, s[46:47]
	s_add_i32 m0, s22, 0x2000
	s_nop 0
	global_load_lds_dwordx4 v132, s[46:47]
	s_mov_b32 m0, s54
	s_nop 0
	global_load_lds_dwordx4 v128, s[26:27]
	s_mov_b32 m0, s55
	s_nop 0
	global_load_lds_dwordx4 v130, s[26:27]
	v_fmamk_f32 v248, v240, 0x3a000000, v227
	v_rsq_f32_e32 v248, v248
	s_nop 0
	v_pk_mul_f32 v[120:121], v[120:121], v[248:249] op_sel_hi:[1,0]
	v_pk_mul_f32 v[122:123], v[122:123], v[248:249] op_sel_hi:[1,0]
	v_pk_mul_f32 v[124:125], v[124:125], v[248:249] op_sel_hi:[1,0]
	v_pk_mul_f32 v[126:127], v[126:127], v[248:249] op_sel_hi:[1,0]
	v_max_f32_e32 v120, 0, v120
	v_max_f32_e32 v121, 0, v121
	v_max_f32_e32 v122, 0, v122
	v_max_f32_e32 v123, 0, v123
	v_max_f32_e32 v124, 0, v124
	v_max_f32_e32 v125, 0, v125
	v_max_f32_e32 v126, 0, v126
	v_max_f32_e32 v127, 0, v127
	v_pk_mul_f32 v[120:121], v[120:121], v[120:121]
	v_pk_mul_f32 v[122:123], v[122:123], v[122:123]
	v_pk_mul_f32 v[124:125], v[124:125], v[124:125]
	v_pk_mul_f32 v[126:127], v[126:127], v[126:127]
	v_cvt_pk_bf16_f32 v124, v124, v125
	v_cvt_pk_bf16_f32 v125, v126, v127
	v_cvt_pk_bf16_f32 v126, v120, v121
	v_cvt_pk_bf16_f32 v127, v122, v123
	global_store_dwordx4 v250, v[124:127], s[98:99]
	v_pk_mul_f32 v[112:113], v[112:113], v[248:249] op_sel_hi:[1,0]
	v_pk_mul_f32 v[114:115], v[114:115], v[248:249] op_sel_hi:[1,0]
	v_pk_mul_f32 v[116:117], v[116:117], v[248:249] op_sel_hi:[1,0]
	v_pk_mul_f32 v[118:119], v[118:119], v[248:249] op_sel_hi:[1,0]
	v_max_f32_e32 v112, 0, v112
	v_max_f32_e32 v113, 0, v113
	v_max_f32_e32 v114, 0, v114
	v_max_f32_e32 v115, 0, v115
	v_max_f32_e32 v116, 0, v116
	v_max_f32_e32 v117, 0, v117
	v_max_f32_e32 v118, 0, v118
	v_max_f32_e32 v119, 0, v119
	v_pk_mul_f32 v[112:113], v[112:113], v[112:113]
;     __device__ __forceinline__ const char* a(const Unit& u) const { return (const char*)A + (size_t)u.pm * 2 * hA(); }
;     __device__ __forceinline__ const char* b(const Unit& u) const { return (const char*)Bt + (size_t)u.pn * 2 * hB() + (size_t)(u.pm >> gshift) * goff; }
;     __device__ __forceinline__ const char* a(const Unit& u) const { return (const char*)A + (size_t)u.pm * 2 * hA(); }
;     __device__ __forceinline__ const char* b(const Unit& u) const { return (const char*)Bt + (size_t)((u.pn >> 4) * 4096 + (u.pn & 15) * 16) * 1024 * 2 + (size_t)(u.pm >> 1) * 512; }
;     __device__ __forceinline__ const char* a(const Unit&) const { return (const char*)A; }
;     __device__ __forceinline__ const char* b(const Unit& u) const { return (const char*)Bt + ((size_t)(((u.pm >> 4) * 1024 + u.pn * 256) * 16 + (u.pm & 15)) * 512) * 2; }
;     __device__ __forceinline__ void operator()(const f32x4 (&acc)[2][2][4][2], const Unit& u, int wr, int wc, int fr, int fq) const {
;     ...
;             for (int m = 0; m < 4; ++m) { const int r = row0 + ai * HALF + m * 16;
;                 bf16_t* rowp = hm ? base + ((size_t)((r >> 12) * 8 + (colt >> 7)) * 4096 + (r & 4095)) * 128 + wc * 32 + 8 * fq : base + (size_t)r * ldc + col0;
;                 float rv = sc; if (RS == 1) rv *= rsv[ai][m]; if (RS == 2) rv *= __builtin_amdgcn_rsqf(rsv[ai][m] * (1.0f / DM) + EPS);
; #pragma unroll
;                 for (int bj = 0; bj < 2; ++bj) { f32x4 v0 = acc[ai][bj][m][0] * rv, v1 = acc[ai][bj][m][1] * rv;
;                     if (CS) { v0 = v0 * cv[bj][0]; v1 = v1 * cv[bj][1]; }
;                     if (ACT == 2) {
; #pragma unroll
;                         for (int e = 0; e < 4; ++e) { float a = v0[e] > 0.f ? v0[e] : 0.f, b = v1[e] > 0.f ? v1[e] : 0.f; v0[e] = a * a; v1[e] = b * b; } }
;                     if (k8) {
;                         u32x2 w8; w8.x = pk_fp8x4(v0); w8.y = pk_fp8x4(v1);
;                         *(u32x2*)((unsigned char*)base + ((size_t)((r >> 12) * 8 + (colt >> 7) + bj) * 4096 + (r & 4095)) * 128 + wc * 32 + 8 * fq) = w8;
;                     } else {
;                     u32x4 w; w.x = cvt_pk_bf16(v0[0], v0[1]); w.y = cvt_pk_bf16(v0[2], v0[3]); w.z = cvt_pk_bf16(v1[0], v1[1]); w.w = cvt_pk_bf16(v1[2], v1[3]);
;                     *(u32x4*)(rowp + bj * bstep) = w; } } }
	v_pk_mul_f32 v[114:115], v[114:115], v[114:115]
	v_pk_mul_f32 v[116:117], v[116:117], v[116:117]
	v_pk_mul_f32 v[118:119], v[118:119], v[118:119]
	v_cvt_pk_bf16_f32 v116, v116, v117
	v_cvt_pk_bf16_f32 v117, v118, v119
	v_cvt_pk_bf16_f32 v118, v112, v113
	v_cvt_pk_bf16_f32 v119, v114, v115
	global_store_dwordx4 v250, v[116:119], s[98:99] offset:256
	s_add_u32 s98, s98, 0x40000
	s_addc_u32 s99, s99, 0
	v_fmamk_f32 v248, v241, 0x3a000000, v227
	v_rsq_f32_e32 v248, v248
	s_nop 0
	v_pk_mul_f32 v[104:105], v[104:105], v[248:249] op_sel_hi:[1,0]
	v_pk_mul_f32 v[106:107], v[106:107], v[248:249] op_sel_hi:[1,0]
	v_pk_mul_f32 v[108:109], v[108:109], v[248:249] op_sel_hi:[1,0]
	v_pk_mul_f32 v[110:111], v[110:111], v[248:249] op_sel_hi:[1,0]
	v_max_f32_e32 v104, 0, v104
	v_max_f32_e32 v105, 0, v105
	v_max_f32_e32 v106, 0, v106
	v_max_f32_e32 v107, 0, v107
	v_max_f32_e32 v108, 0, v108
	v_max_f32_e32 v109, 0, v109
	v_max_f32_e32 v110, 0, v110
	v_max_f32_e32 v111, 0, v111
	v_pk_mul_f32 v[104:105], v[104:105], v[104:105]
	v_pk_mul_f32 v[106:107], v[106:107], v[106:107]
	v_pk_mul_f32 v[108:109], v[108:109], v[108:109]
	v_pk_mul_f32 v[110:111], v[110:111], v[110:111]
	v_cvt_pk_bf16_f32 v108, v108, v109
	v_cvt_pk_bf16_f32 v109, v110, v111
	v_cvt_pk_bf16_f32 v110, v104, v105
	v_cvt_pk_bf16_f32 v111, v106, v107
	global_store_dwordx4 v250, v[108:111], s[98:99]
	v_pk_mul_f32 v[96:97], v[96:97], v[248:249] op_sel_hi:[1,0]
	v_pk_mul_f32 v[98:99], v[98:99], v[248:249] op_sel_hi:[1,0]
	v_pk_mul_f32 v[100:101], v[100:101], v[248:249] op_sel_hi:[1,0]
	v_pk_mul_f32 v[102:103], v[102:103], v[248:249] op_sel_hi:[1,0]
	v_max_f32_e32 v96, 0, v96
	v_max_f32_e32 v97, 0, v97
	v_max_f32_e32 v98, 0, v98
	v_max_f32_e32 v99, 0, v99
	v_max_f32_e32 v100, 0, v100
	v_max_f32_e32 v101, 0, v101
	v_max_f32_e32 v102, 0, v102
	v_max_f32_e32 v103, 0, v103
	v_pk_mul_f32 v[96:97], v[96:97], v[96:97]
	v_pk_mul_f32 v[98:99], v[98:99], v[98:99]
	v_pk_mul_f32 v[100:101], v[100:101], v[100:101]
	v_pk_mul_f32 v[102:103], v[102:103], v[102:103]
	v_cvt_pk_bf16_f32 v100, v100, v101
	v_cvt_pk_bf16_f32 v101, v102, v103
	v_cvt_pk_bf16_f32 v102, v96, v97
	v_cvt_pk_bf16_f32 v103, v98, v99
	global_store_dwordx4 v250, v[100:103], s[98:99] offset:256
	s_add_u32 s98, s98, 0x40000
	s_addc_u32 s99, s99, 0
	s_waitcnt vmcnt(12)
	s_waitcnt lgkmcnt(0)
	s_barrier
;     __device__ __forceinline__ const char* a(const Unit& u) const { return (const char*)A + (size_t)u.pm * 2 * hA(); }
;     __device__ __forceinline__ const char* b(const Unit& u) const { return (const char*)Bt + (size_t)u.pn * 2 * hB() + (size_t)(u.pm >> gshift) * goff; }
;     __device__ __forceinline__ const char* a(const Unit& u) const { return (const char*)A + (size_t)u.pm * 2 * hA(); }
;     __device__ __forceinline__ const char* b(const Unit& u) const { return (const char*)Bt + (size_t)((u.pn >> 4) * 4096 + (u.pn & 15) * 16) * 1024 * 2 + (size_t)(u.pm >> 1) * 512; }
;     __device__ __forceinline__ const char* a(const Unit&) const { return (const char*)A; }
;     __device__ __forceinline__ void operator()(const f32x4 (&acc)[2][2][4][2], const Unit& u, int wr, int wc, int fr, int fq) const {
;     ...
;             for (int m = 0; m < 4; ++m) { const int r = row0 + ai * HALF + m * 16;
;                 bf16_t* rowp = hm ? base + ((size_t)((r >> 12) * 8 + (colt >> 7)) * 4096 + (r & 4095)) * 128 + wc * 32 + 8 * fq : base + (size_t)r * ldc + col0;
;                 float rv = sc; if (RS == 1) rv *= rsv[ai][m]; if (RS == 2) rv *= __builtin_amdgcn_rsqf(rsv[ai][m] * (1.0f / DM) + EPS);
; #pragma unroll
;                 for (int bj = 0; bj < 2; ++bj) { f32x4 v0 = acc[ai][bj][m][0] * rv, v1 = acc[ai][bj][m][1] * rv;
;                     if (CS) { v0 = v0 * cv[bj][0]; v1 = v1 * cv[bj][1]; }
;                     if (ACT == 2) {
; #pragma unroll
;                         for (int e = 0; e < 4; ++e) { float a = v0[e] > 0.f ? v0[e] : 0.f, b = v1[e] > 0.f ? v1[e] : 0.f; v0[e] = a * a; v1[e] = b * b; } }
;                     if (k8) {
;                         u32x2 w8; w8.x = pk_fp8x4(v0); w8.y = pk_fp8x4(v1);
;                         *(u32x2*)((unsigned char*)base + ((size_t)((r >> 12) * 8 + (colt >> 7) + bj) * 4096 + (r & 4095)) * 128 + wc * 32 + 8 * fq) = w8;
;                     } else {
;                     u32x4 w; w.x = cvt_pk_bf16(v0[0], v0[1]); w.y = cvt_pk_bf16(v0[2], v0[3]); w.z = cvt_pk_bf16(v1[0], v1[1]); w.w = cvt_pk_bf16(v1[2], v1[3]);
;                     *(u32x4*)(rowp + bj * bstep) = w; } } }
;     ...
;         { const int tmid = (TSW > 0 && TSW < nt) ? TSW : nt;
;           _Pragma("unroll 1") for (int t = 0; t < tmid; t += 2) { PG8_BODY(PG8_MMA) }
	s_setprio 1
	s_waitcnt lgkmcnt(0)
	v_mfma_f32_16x16x32_bf16 v[60:63], v[134:137], v[166:169], v[60:63]
	v_fmamk_f32 v248, v242, 0x3a000000, v227
	v_rsq_f32_e32 v248, v248
	s_nop 0
	v_mfma_f32_16x16x32_bf16 v[56:59], v[142:145], v[166:169], v[56:59]
	v_pk_mul_f32 v[88:89], v[88:89], v[248:249] op_sel_hi:[1,0]
	v_pk_mul_f32 v[90:91], v[90:91], v[248:249] op_sel_hi:[1,0]
	v_pk_mul_f32 v[92:93], v[92:93], v[248:249] op_sel_hi:[1,0]
	v_mfma_f32_16x16x32_bf16 v[44:47], v[134:137], v[174:177], v[44:47]
	v_pk_mul_f32 v[94:95], v[94:95], v[248:249] op_sel_hi:[1,0]
	v_max_f32_e32 v88, 0, v88
	v_max_f32_e32 v89, 0, v89
	v_mfma_f32_16x16x32_bf16 v[40:43], v[142:145], v[174:177], v[40:43]
	v_max_f32_e32 v90, 0, v90
	v_max_f32_e32 v91, 0, v91
	v_max_f32_e32 v92, 0, v92
	v_mfma_f32_16x16x32_bf16 v[28:31], v[134:137], v[182:185], v[28:31]
	v_max_f32_e32 v93, 0, v93
	v_max_f32_e32 v94, 0, v94
	v_max_f32_e32 v95, 0, v95
	v_mfma_f32_16x16x32_bf16 v[24:27], v[142:145], v[182:185], v[24:27]
	v_pk_mul_f32 v[88:89], v[88:89], v[88:89]
	v_pk_mul_f32 v[90:91], v[90:91], v[90:91]
	v_pk_mul_f32 v[92:93], v[92:93], v[92:93]
	v_mfma_f32_16x16x32_bf16 v[12:15], v[134:137], v[202:205], v[12:15]
	v_pk_mul_f32 v[94:95], v[94:95], v[94:95]
	v_cvt_pk_bf16_f32 v92, v92, v93
	v_cvt_pk_bf16_f32 v93, v94, v95
	v_mfma_f32_16x16x32_bf16 v[8:11], v[142:145], v[202:205], v[8:11]
	v_cvt_pk_bf16_f32 v94, v88, v89
	v_cvt_pk_bf16_f32 v95, v90, v91
	global_store_dwordx4 v250, v[92:95], s[98:99]
	v_mfma_f32_16x16x32_bf16 v[60:63], v[138:141], v[170:173], v[60:63]
	v_pk_mul_f32 v[80:81], v[80:81], v[248:249] op_sel_hi:[1,0]
	v_pk_mul_f32 v[82:83], v[82:83], v[248:249] op_sel_hi:[1,0]
	v_pk_mul_f32 v[84:85], v[84:85], v[248:249] op_sel_hi:[1,0]
	v_mfma_f32_16x16x32_bf16 v[56:59], v[146:149], v[170:173], v[56:59]
	v_pk_mul_f32 v[86:87], v[86:87], v[248:249] op_sel_hi:[1,0]
	v_max_f32_e32 v80, 0, v80
	v_max_f32_e32 v81, 0, v81
	v_mfma_f32_16x16x32_bf16 v[44:47], v[138:141], v[178:181], v[44:47]
	v_max_f32_e32 v82, 0, v82
	v_max_f32_e32 v83, 0, v83
	v_max_f32_e32 v84, 0, v84
	v_mfma_f32_16x16x32_bf16 v[40:43], v[146:149], v[178:181], v[40:43]
	v_max_f32_e32 v85, 0, v85
	v_max_f32_e32 v86, 0, v86
	v_max_f32_e32 v87, 0, v87
	v_mfma_f32_16x16x32_bf16 v[28:31], v[138:141], v[186:189], v[28:31]
	v_pk_mul_f32 v[80:81], v[80:81], v[80:81]
	v_pk_mul_f32 v[82:83], v[82:83], v[82:83]
	v_pk_mul_f32 v[84:85], v[84:85], v[84:85]
	v_mfma_f32_16x16x32_bf16 v[24:27], v[146:149], v[186:189], v[24:27]
	v_pk_mul_f32 v[86:87], v[86:87], v[86:87]
	v_cvt_pk_bf16_f32 v84, v84, v85
	v_cvt_pk_bf16_f32 v85, v86, v87
	v_mfma_f32_16x16x32_bf16 v[12:15], v[138:141], v[206:209], v[12:15]
	v_cvt_pk_bf16_f32 v86, v80, v81
	v_cvt_pk_bf16_f32 v87, v82, v83
	global_store_dwordx4 v250, v[84:87], s[98:99] offset:256
	v_mfma_f32_16x16x32_bf16 v[8:11], v[146:149], v[206:209], v[8:11]
	s_add_u32 s98, s98, 0x40000
	s_addc_u32 s99, s99, 0
	v_fmamk_f32 v248, v243, 0x3a000000, v227
	s_setprio 0
	s_setprio 1
	v_mfma_f32_16x16x32_bf16 v[52:55], v[150:153], v[166:169], v[52:55]
	v_rsq_f32_e32 v248, v248
	s_nop 0
	v_pk_mul_f32 v[72:73], v[72:73], v[248:249] op_sel_hi:[1,0]
	v_mfma_f32_16x16x32_bf16 v[48:51], v[158:161], v[166:169], v[48:51]
	v_pk_mul_f32 v[74:75], v[74:75], v[248:249] op_sel_hi:[1,0]
	v_pk_mul_f32 v[76:77], v[76:77], v[248:249] op_sel_hi:[1,0]
	v_pk_mul_f32 v[78:79], v[78:79], v[248:249] op_sel_hi:[1,0]
	v_mfma_f32_16x16x32_bf16 v[36:39], v[150:153], v[174:177], v[36:39]
	v_max_f32_e32 v72, 0, v72
	v_max_f32_e32 v73, 0, v73
	v_max_f32_e32 v74, 0, v74
	v_mfma_f32_16x16x32_bf16 v[32:35], v[158:161], v[174:177], v[32:35]
	v_max_f32_e32 v75, 0, v75
	v_max_f32_e32 v76, 0, v76
	v_max_f32_e32 v77, 0, v77
	v_mfma_f32_16x16x32_bf16 v[20:23], v[150:153], v[182:185], v[20:23]
	v_max_f32_e32 v78, 0, v78
	v_max_f32_e32 v79, 0, v79
	v_pk_mul_f32 v[72:73], v[72:73], v[72:73]
	v_mfma_f32_16x16x32_bf16 v[16:19], v[158:161], v[182:185], v[16:19]
	v_pk_mul_f32 v[74:75], v[74:75], v[74:75]
	v_pk_mul_f32 v[76:77], v[76:77], v[76:77]
	v_pk_mul_f32 v[78:79], v[78:79], v[78:79]
	v_mfma_f32_16x16x32_bf16 v[4:7], v[150:153], v[202:205], v[4:7]
	v_cvt_pk_bf16_f32 v76, v76, v77
	v_cvt_pk_bf16_f32 v77, v78, v79
	v_cvt_pk_bf16_f32 v78, v72, v73
	v_mfma_f32_16x16x32_bf16 v[0:3], v[158:161], v[202:205], v[0:3]
	v_cvt_pk_bf16_f32 v79, v74, v75
	global_store_dwordx4 v250, v[76:79], s[98:99]
	v_pk_mul_f32 v[64:65], v[64:65], v[248:249] op_sel_hi:[1,0]
	v_mfma_f32_16x16x32_bf16 v[52:55], v[154:157], v[170:173], v[52:55]
	v_pk_mul_f32 v[66:67], v[66:67], v[248:249] op_sel_hi:[1,0]
	v_pk_mul_f32 v[68:69], v[68:69], v[248:249] op_sel_hi:[1,0]
	v_pk_mul_f32 v[70:71], v[70:71], v[248:249] op_sel_hi:[1,0]
	v_mfma_f32_16x16x32_bf16 v[48:51], v[162:165], v[170:173], v[48:51]
	v_max_f32_e32 v64, 0, v64
	v_max_f32_e32 v65, 0, v65
	v_max_f32_e32 v66, 0, v66
	v_mfma_f32_16x16x32_bf16 v[36:39], v[154:157], v[178:181], v[36:39]
	v_max_f32_e32 v67, 0, v67
	v_max_f32_e32 v68, 0, v68
	v_max_f32_e32 v69, 0, v69
	v_mfma_f32_16x16x32_bf16 v[32:35], v[162:165], v[178:181], v[32:35]
	v_max_f32_e32 v70, 0, v70
	v_max_f32_e32 v71, 0, v71
	v_pk_mul_f32 v[64:65], v[64:65], v[64:65]
	v_mfma_f32_16x16x32_bf16 v[20:23], v[154:157], v[186:189], v[20:23]
	v_pk_mul_f32 v[66:67], v[66:67], v[66:67]
	v_pk_mul_f32 v[68:69], v[68:69], v[68:69]
	v_pk_mul_f32 v[70:71], v[70:71], v[70:71]
	v_mfma_f32_16x16x32_bf16 v[16:19], v[162:165], v[186:189], v[16:19]
	v_cvt_pk_bf16_f32 v68, v68, v69
	v_cvt_pk_bf16_f32 v69, v70, v71
	v_cvt_pk_bf16_f32 v70, v64, v65
	v_mfma_f32_16x16x32_bf16 v[4:7], v[154:157], v[206:209], v[4:7]
	v_cvt_pk_bf16_f32 v71, v66, v67
	global_store_dwordx4 v250, v[68:71], s[98:99] offset:256
	s_add_u32 s98, s98, 0x40000
	v_mfma_f32_16x16x32_bf16 v[0:3], v[162:165], v[206:209], v[0:3]
	s_addc_u32 s99, s99, 0
	s_setprio 0
	s_barrier
	s_branch .LBB0_707
mk_p5_exit:
	s_and_b64 vcc, exec, s[82:83]
	s_cbranch_vccz .LBB0_719
	s_barrier
